# P2 gelu/silu epilogue bodies re-emitted with fewer VALU ops (packed scale/add; abs-modifier fma + max/fma select), 4 pairs in lockstep
# speedup vs baseline: 1.0266x; 1.0032x over previous
.LBB0_294:
	s_cmp_gt_i32 s59, 1
	s_cselect_b64 s[80:81], -1, 0
	s_cmp_lt_i32 s59, 2
	s_mov_b64 s[82:83], -1
	s_cbranch_scc1 .LBB0_296
	v_mov_b32_e32 v188, 0xbfb8aa3b
	v_pk_mul_f32 v[148:149], v[124:125], v[188:189] op_sel_hi:[1,0]
	v_pk_mul_f32 v[150:151], v[126:127], v[188:189] op_sel_hi:[1,0]
	v_pk_mul_f32 v[152:153], v[92:93], v[188:189] op_sel_hi:[1,0]
	v_pk_mul_f32 v[154:155], v[94:95], v[188:189] op_sel_hi:[1,0]
	v_exp_f32_e32 v148, v148
	v_exp_f32_e32 v150, v150
	v_exp_f32_e32 v152, v152
	v_exp_f32_e32 v154, v154
	v_exp_f32_e32 v149, v149
	v_exp_f32_e32 v151, v151
	v_exp_f32_e32 v153, v153
	v_exp_f32_e32 v155, v155
	v_pk_add_f32 v[148:149], v[148:149], 1.0 op_sel_hi:[1,0]
	v_pk_add_f32 v[150:151], v[150:151], 1.0 op_sel_hi:[1,0]
	v_pk_add_f32 v[152:153], v[152:153], 1.0 op_sel_hi:[1,0]
	v_pk_add_f32 v[154:155], v[154:155], 1.0 op_sel_hi:[1,0]
	v_rcp_f32_e32 v148, v148
	v_rcp_f32_e32 v150, v150
	v_rcp_f32_e32 v152, v152
	v_rcp_f32_e32 v154, v154
	v_rcp_f32_e32 v149, v149
	v_rcp_f32_e32 v151, v151
	v_rcp_f32_e32 v153, v153
	v_rcp_f32_e32 v155, v155
	v_pk_mul_f32 v[148:149], v[124:125], v[148:149]
	v_pk_mul_f32 v[150:151], v[126:127], v[150:151]
	v_pk_mul_f32 v[152:153], v[92:93], v[152:153]
	v_pk_mul_f32 v[154:155], v[94:95], v[154:155]
	s_mov_b64 s[82:83], 0
.LBB0_296:
	s_andn2_b64 vcc, exec, s[82:83]
	s_cbranch_vccnz .LBB0_298
	v_mov_b32_e32 v188, s12
	v_fma_f32 v172, |v124|, s8, 1.0
	v_fma_f32 v174, |v126|, s8, 1.0
	v_fma_f32 v176, |v92|, s8, 1.0
	v_fma_f32 v178, |v94|, s8, 1.0
	v_fma_f32 v173, |v125|, s8, 1.0
	v_fma_f32 v175, |v127|, s8, 1.0
	v_fma_f32 v177, |v93|, s8, 1.0
	v_fma_f32 v179, |v95|, s8, 1.0
	v_pk_mul_f32 v[148:149], v[124:125], v[124:125]
	v_pk_mul_f32 v[150:151], v[126:127], v[126:127]
	v_pk_mul_f32 v[152:153], v[92:93], v[92:93]
	v_pk_mul_f32 v[154:155], v[94:95], v[94:95]
	v_rcp_f32_e32 v172, v172
	v_rcp_f32_e32 v174, v174
	v_rcp_f32_e32 v176, v176
	v_rcp_f32_e32 v178, v178
	v_rcp_f32_e32 v173, v173
	v_rcp_f32_e32 v175, v175
	v_rcp_f32_e32 v177, v177
	v_rcp_f32_e32 v179, v179
	v_pk_mul_f32 v[148:149], v[148:149], s[54:55] op_sel_hi:[1,0]
	v_pk_mul_f32 v[150:151], v[150:151], s[54:55] op_sel_hi:[1,0]
	v_pk_mul_f32 v[152:153], v[152:153], s[54:55] op_sel_hi:[1,0]
	v_pk_mul_f32 v[154:155], v[154:155], s[54:55] op_sel_hi:[1,0]
	v_pk_fma_f32 v[180:181], v[172:173], s[10:11], v[188:189] op_sel_hi:[1,0,0]
	v_pk_fma_f32 v[182:183], v[174:175], s[10:11], v[188:189] op_sel_hi:[1,0,0]
	v_pk_fma_f32 v[184:185], v[176:177], s[10:11], v[188:189] op_sel_hi:[1,0,0]
	v_pk_fma_f32 v[186:187], v[178:179], s[10:11], v[188:189] op_sel_hi:[1,0,0]
	v_exp_f32_e32 v148, v148
	v_exp_f32_e32 v150, v150
	v_exp_f32_e32 v152, v152
	v_exp_f32_e32 v154, v154
	v_exp_f32_e32 v149, v149
	v_exp_f32_e32 v151, v151
	v_exp_f32_e32 v153, v153
	v_exp_f32_e32 v155, v155
	v_pk_fma_f32 v[180:181], v[172:173], v[180:181], s[14:15] op_sel_hi:[1,1,0]
	v_pk_fma_f32 v[182:183], v[174:175], v[182:183], s[14:15] op_sel_hi:[1,1,0]
	v_pk_fma_f32 v[184:185], v[176:177], v[184:185], s[14:15] op_sel_hi:[1,1,0]
	v_pk_fma_f32 v[186:187], v[178:179], v[186:187], s[14:15] op_sel_hi:[1,1,0]
	v_pk_fma_f32 v[180:181], v[172:173], v[180:181], s[18:19] op_sel_hi:[1,1,0]
	v_pk_fma_f32 v[182:183], v[174:175], v[182:183], s[18:19] op_sel_hi:[1,1,0]
	v_pk_fma_f32 v[184:185], v[176:177], v[184:185], s[18:19] op_sel_hi:[1,1,0]
	v_pk_fma_f32 v[186:187], v[178:179], v[186:187], s[18:19] op_sel_hi:[1,1,0]
	v_pk_fma_f32 v[180:181], v[172:173], v[180:181], s[36:37] op_sel_hi:[1,1,0]
	v_pk_fma_f32 v[182:183], v[174:175], v[182:183], s[36:37] op_sel_hi:[1,1,0]
	v_pk_fma_f32 v[184:185], v[176:177], v[184:185], s[36:37] op_sel_hi:[1,1,0]
	v_pk_fma_f32 v[186:187], v[178:179], v[186:187], s[36:37] op_sel_hi:[1,1,0]
	v_pk_mul_f32 v[180:181], v[172:173], v[180:181]
	v_pk_mul_f32 v[182:183], v[174:175], v[182:183]
	v_pk_mul_f32 v[184:185], v[176:177], v[184:185]
	v_pk_mul_f32 v[186:187], v[178:179], v[186:187]
	v_pk_mul_f32 v[180:181], v[148:149], v[180:181]
	v_pk_mul_f32 v[182:183], v[150:151], v[182:183]
	v_pk_mul_f32 v[184:185], v[152:153], v[184:185]
	v_pk_mul_f32 v[186:187], v[154:155], v[186:187]
	v_max_f32_e32 v148, 0, v124
	v_max_f32_e32 v150, 0, v126
	v_max_f32_e32 v152, 0, v92
	v_max_f32_e32 v154, 0, v94
	v_max_f32_e32 v149, 0, v125
	v_max_f32_e32 v151, 0, v127
	v_max_f32_e32 v153, 0, v93
	v_max_f32_e32 v155, 0, v95
	v_fma_f32 v148, -|v124|, v180, v148
	v_fma_f32 v150, -|v126|, v182, v150
	v_fma_f32 v152, -|v92|, v184, v152
	v_fma_f32 v154, -|v94|, v186, v154
	v_fma_f32 v149, -|v125|, v181, v149
	v_fma_f32 v151, -|v127|, v183, v151
	v_fma_f32 v153, -|v93|, v185, v153
	v_fma_f32 v155, -|v95|, v187, v155
.LBB0_298:
	v_lshlrev_b32_e32 v136, 1, v163
	v_lshl_or_b32 v136, s57, 9, v136
	v_lshl_add_u64 v[146:147], s[0:1], 0, v[136:137]
	v_lshlrev_b64 v[156:157], 10, v[144:145]
	v_cndmask_b32_e64 v136, 0, 1, s[80:81]
	v_lshl_add_u64 v[146:147], v[146:147], 0, v[156:157]
	v_cvt_pk_bf16_f32 v148, v148, v149
	v_cvt_pk_bf16_f32 v149, v150, v151
	v_cvt_pk_bf16_f32 v150, v152, v153
	v_cvt_pk_bf16_f32 v151, v154, v155
	v_cmp_ne_u32_e64 s[0:1], 1, v136
	s_andn2_b64 vcc, exec, s[80:81]
	s_mov_b64 s[80:81], -1
	global_store_dwordx4 v[146:147], v[148:151], off
	s_cbranch_vccnz .LBB0_300
	v_mov_b32_e32 v188, 0xbfb8aa3b
	v_pk_mul_f32 v[148:149], v[60:61], v[188:189] op_sel_hi:[1,0]
	v_pk_mul_f32 v[150:151], v[62:63], v[188:189] op_sel_hi:[1,0]
	v_pk_mul_f32 v[152:153], v[28:29], v[188:189] op_sel_hi:[1,0]
	v_pk_mul_f32 v[154:155], v[30:31], v[188:189] op_sel_hi:[1,0]
	v_exp_f32_e32 v148, v148
	v_exp_f32_e32 v150, v150
	v_exp_f32_e32 v152, v152
	v_exp_f32_e32 v154, v154
	v_exp_f32_e32 v149, v149
	v_exp_f32_e32 v151, v151
	v_exp_f32_e32 v153, v153
	v_exp_f32_e32 v155, v155
	v_pk_add_f32 v[148:149], v[148:149], 1.0 op_sel_hi:[1,0]
	v_pk_add_f32 v[150:151], v[150:151], 1.0 op_sel_hi:[1,0]
	v_pk_add_f32 v[152:153], v[152:153], 1.0 op_sel_hi:[1,0]
	v_pk_add_f32 v[154:155], v[154:155], 1.0 op_sel_hi:[1,0]
	v_rcp_f32_e32 v148, v148
	v_rcp_f32_e32 v150, v150
	v_rcp_f32_e32 v152, v152
	v_rcp_f32_e32 v154, v154
	v_rcp_f32_e32 v149, v149
	v_rcp_f32_e32 v151, v151
	v_rcp_f32_e32 v153, v153
	v_rcp_f32_e32 v155, v155
	v_pk_mul_f32 v[148:149], v[60:61], v[148:149]
	v_pk_mul_f32 v[150:151], v[62:63], v[150:151]
	v_pk_mul_f32 v[152:153], v[28:29], v[152:153]
	v_pk_mul_f32 v[154:155], v[30:31], v[154:155]
	s_mov_b64 s[80:81], 0
.LBB0_300:
	s_andn2_b64 vcc, exec, s[80:81]
	s_cbranch_vccnz .LBB0_302
	v_mov_b32_e32 v188, s12
	v_fma_f32 v172, |v60|, s8, 1.0
	v_fma_f32 v174, |v62|, s8, 1.0
	v_fma_f32 v176, |v28|, s8, 1.0
	v_fma_f32 v178, |v30|, s8, 1.0
	v_fma_f32 v173, |v61|, s8, 1.0
	v_fma_f32 v175, |v63|, s8, 1.0
	v_fma_f32 v177, |v29|, s8, 1.0
	v_fma_f32 v179, |v31|, s8, 1.0
	v_pk_mul_f32 v[148:149], v[60:61], v[60:61]
	v_pk_mul_f32 v[150:151], v[62:63], v[62:63]
	v_pk_mul_f32 v[152:153], v[28:29], v[28:29]
	v_pk_mul_f32 v[154:155], v[30:31], v[30:31]
	v_rcp_f32_e32 v172, v172
	v_rcp_f32_e32 v174, v174
	v_rcp_f32_e32 v176, v176
	v_rcp_f32_e32 v178, v178
	v_rcp_f32_e32 v173, v173
	v_rcp_f32_e32 v175, v175
	v_rcp_f32_e32 v177, v177
	v_rcp_f32_e32 v179, v179
	v_pk_mul_f32 v[148:149], v[148:149], s[54:55] op_sel_hi:[1,0]
	v_pk_mul_f32 v[150:151], v[150:151], s[54:55] op_sel_hi:[1,0]
	v_pk_mul_f32 v[152:153], v[152:153], s[54:55] op_sel_hi:[1,0]
	v_pk_mul_f32 v[154:155], v[154:155], s[54:55] op_sel_hi:[1,0]
	v_pk_fma_f32 v[180:181], v[172:173], s[10:11], v[188:189] op_sel_hi:[1,0,0]
	v_pk_fma_f32 v[182:183], v[174:175], s[10:11], v[188:189] op_sel_hi:[1,0,0]
	v_pk_fma_f32 v[184:185], v[176:177], s[10:11], v[188:189] op_sel_hi:[1,0,0]
	v_pk_fma_f32 v[186:187], v[178:179], s[10:11], v[188:189] op_sel_hi:[1,0,0]
	v_exp_f32_e32 v148, v148
	v_exp_f32_e32 v150, v150
	v_exp_f32_e32 v152, v152
	v_exp_f32_e32 v154, v154
	v_exp_f32_e32 v149, v149
	v_exp_f32_e32 v151, v151
	v_exp_f32_e32 v153, v153
	v_exp_f32_e32 v155, v155
	v_pk_fma_f32 v[180:181], v[172:173], v[180:181], s[14:15] op_sel_hi:[1,1,0]
	v_pk_fma_f32 v[182:183], v[174:175], v[182:183], s[14:15] op_sel_hi:[1,1,0]
	v_pk_fma_f32 v[184:185], v[176:177], v[184:185], s[14:15] op_sel_hi:[1,1,0]
	v_pk_fma_f32 v[186:187], v[178:179], v[186:187], s[14:15] op_sel_hi:[1,1,0]
	v_pk_fma_f32 v[180:181], v[172:173], v[180:181], s[18:19] op_sel_hi:[1,1,0]
	v_pk_fma_f32 v[182:183], v[174:175], v[182:183], s[18:19] op_sel_hi:[1,1,0]
	v_pk_fma_f32 v[184:185], v[176:177], v[184:185], s[18:19] op_sel_hi:[1,1,0]
	v_pk_fma_f32 v[186:187], v[178:179], v[186:187], s[18:19] op_sel_hi:[1,1,0]
	v_pk_fma_f32 v[180:181], v[172:173], v[180:181], s[36:37] op_sel_hi:[1,1,0]
	v_pk_fma_f32 v[182:183], v[174:175], v[182:183], s[36:37] op_sel_hi:[1,1,0]
	v_pk_fma_f32 v[184:185], v[176:177], v[184:185], s[36:37] op_sel_hi:[1,1,0]
	v_pk_fma_f32 v[186:187], v[178:179], v[186:187], s[36:37] op_sel_hi:[1,1,0]
	v_pk_mul_f32 v[180:181], v[172:173], v[180:181]
	v_pk_mul_f32 v[182:183], v[174:175], v[182:183]
	v_pk_mul_f32 v[184:185], v[176:177], v[184:185]
	v_pk_mul_f32 v[186:187], v[178:179], v[186:187]
	v_pk_mul_f32 v[180:181], v[148:149], v[180:181]
	v_pk_mul_f32 v[182:183], v[150:151], v[182:183]
	v_pk_mul_f32 v[184:185], v[152:153], v[184:185]
	v_pk_mul_f32 v[186:187], v[154:155], v[186:187]
	v_max_f32_e32 v148, 0, v60
	v_max_f32_e32 v150, 0, v62
	v_max_f32_e32 v152, 0, v28
	v_max_f32_e32 v154, 0, v30
	v_max_f32_e32 v149, 0, v61
	v_max_f32_e32 v151, 0, v63
	v_max_f32_e32 v153, 0, v29
	v_max_f32_e32 v155, 0, v31
	v_fma_f32 v148, -|v60|, v180, v148
	v_fma_f32 v150, -|v62|, v182, v150
	v_fma_f32 v152, -|v28|, v184, v152
	v_fma_f32 v154, -|v30|, v186, v154
	v_fma_f32 v149, -|v61|, v181, v149
	v_fma_f32 v151, -|v63|, v183, v151
	v_fma_f32 v153, -|v29|, v185, v153
	v_fma_f32 v155, -|v31|, v187, v155
.LBB0_302:
	v_cvt_pk_bf16_f32 v148, v148, v149
	v_cvt_pk_bf16_f32 v149, v150, v151
	v_cvt_pk_bf16_f32 v150, v152, v153
	v_cvt_pk_bf16_f32 v151, v154, v155
	s_and_b64 vcc, exec, s[0:1]
	s_mov_b64 s[80:81], -1
	global_store_dwordx4 v[146:147], v[148:151], off offset:256
	s_cbranch_vccnz .LBB0_304
	v_mov_b32_e32 v188, 0xbfb8aa3b
	v_pk_mul_f32 v[148:149], v[120:121], v[188:189] op_sel_hi:[1,0]
	v_pk_mul_f32 v[150:151], v[122:123], v[188:189] op_sel_hi:[1,0]
	v_pk_mul_f32 v[152:153], v[88:89], v[188:189] op_sel_hi:[1,0]
	v_pk_mul_f32 v[154:155], v[90:91], v[188:189] op_sel_hi:[1,0]
	v_exp_f32_e32 v148, v148
	v_exp_f32_e32 v150, v150
	v_exp_f32_e32 v152, v152
	v_exp_f32_e32 v154, v154
	v_exp_f32_e32 v149, v149
	v_exp_f32_e32 v151, v151
	v_exp_f32_e32 v153, v153
	v_exp_f32_e32 v155, v155
	v_pk_add_f32 v[148:149], v[148:149], 1.0 op_sel_hi:[1,0]
	v_pk_add_f32 v[150:151], v[150:151], 1.0 op_sel_hi:[1,0]
	v_pk_add_f32 v[152:153], v[152:153], 1.0 op_sel_hi:[1,0]
	v_pk_add_f32 v[154:155], v[154:155], 1.0 op_sel_hi:[1,0]
	v_rcp_f32_e32 v148, v148
	v_rcp_f32_e32 v150, v150
	v_rcp_f32_e32 v152, v152
	v_rcp_f32_e32 v154, v154
	v_rcp_f32_e32 v149, v149
	v_rcp_f32_e32 v151, v151
	v_rcp_f32_e32 v153, v153
	v_rcp_f32_e32 v155, v155
	v_pk_mul_f32 v[148:149], v[120:121], v[148:149]
	v_pk_mul_f32 v[150:151], v[122:123], v[150:151]
	v_pk_mul_f32 v[152:153], v[88:89], v[152:153]
	v_pk_mul_f32 v[154:155], v[90:91], v[154:155]
	s_mov_b64 s[80:81], 0
.LBB0_304:
	s_andn2_b64 vcc, exec, s[80:81]
	s_cbranch_vccnz .LBB0_306
	v_mov_b32_e32 v188, s12
	v_fma_f32 v172, |v120|, s8, 1.0
	v_fma_f32 v174, |v122|, s8, 1.0
	v_fma_f32 v176, |v88|, s8, 1.0
	v_fma_f32 v178, |v90|, s8, 1.0
	v_fma_f32 v173, |v121|, s8, 1.0
	v_fma_f32 v175, |v123|, s8, 1.0
	v_fma_f32 v177, |v89|, s8, 1.0
	v_fma_f32 v179, |v91|, s8, 1.0
	v_pk_mul_f32 v[148:149], v[120:121], v[120:121]
	v_pk_mul_f32 v[150:151], v[122:123], v[122:123]
	v_pk_mul_f32 v[152:153], v[88:89], v[88:89]
	v_pk_mul_f32 v[154:155], v[90:91], v[90:91]
	v_rcp_f32_e32 v172, v172
	v_rcp_f32_e32 v174, v174
	v_rcp_f32_e32 v176, v176
	v_rcp_f32_e32 v178, v178
	v_rcp_f32_e32 v173, v173
	v_rcp_f32_e32 v175, v175
	v_rcp_f32_e32 v177, v177
	v_rcp_f32_e32 v179, v179
	v_pk_mul_f32 v[148:149], v[148:149], s[54:55] op_sel_hi:[1,0]
	v_pk_mul_f32 v[150:151], v[150:151], s[54:55] op_sel_hi:[1,0]
	v_pk_mul_f32 v[152:153], v[152:153], s[54:55] op_sel_hi:[1,0]
	v_pk_mul_f32 v[154:155], v[154:155], s[54:55] op_sel_hi:[1,0]
	v_pk_fma_f32 v[180:181], v[172:173], s[10:11], v[188:189] op_sel_hi:[1,0,0]
	v_pk_fma_f32 v[182:183], v[174:175], s[10:11], v[188:189] op_sel_hi:[1,0,0]
	v_pk_fma_f32 v[184:185], v[176:177], s[10:11], v[188:189] op_sel_hi:[1,0,0]
	v_pk_fma_f32 v[186:187], v[178:179], s[10:11], v[188:189] op_sel_hi:[1,0,0]
	v_exp_f32_e32 v148, v148
	v_exp_f32_e32 v150, v150
	v_exp_f32_e32 v152, v152
	v_exp_f32_e32 v154, v154
	v_exp_f32_e32 v149, v149
	v_exp_f32_e32 v151, v151
	v_exp_f32_e32 v153, v153
	v_exp_f32_e32 v155, v155
	v_pk_fma_f32 v[180:181], v[172:173], v[180:181], s[14:15] op_sel_hi:[1,1,0]
	v_pk_fma_f32 v[182:183], v[174:175], v[182:183], s[14:15] op_sel_hi:[1,1,0]
	v_pk_fma_f32 v[184:185], v[176:177], v[184:185], s[14:15] op_sel_hi:[1,1,0]
	v_pk_fma_f32 v[186:187], v[178:179], v[186:187], s[14:15] op_sel_hi:[1,1,0]
	v_pk_fma_f32 v[180:181], v[172:173], v[180:181], s[18:19] op_sel_hi:[1,1,0]
	v_pk_fma_f32 v[182:183], v[174:175], v[182:183], s[18:19] op_sel_hi:[1,1,0]
	v_pk_fma_f32 v[184:185], v[176:177], v[184:185], s[18:19] op_sel_hi:[1,1,0]
	v_pk_fma_f32 v[186:187], v[178:179], v[186:187], s[18:19] op_sel_hi:[1,1,0]
	v_pk_fma_f32 v[180:181], v[172:173], v[180:181], s[36:37] op_sel_hi:[1,1,0]
	v_pk_fma_f32 v[182:183], v[174:175], v[182:183], s[36:37] op_sel_hi:[1,1,0]
	v_pk_fma_f32 v[184:185], v[176:177], v[184:185], s[36:37] op_sel_hi:[1,1,0]
	v_pk_fma_f32 v[186:187], v[178:179], v[186:187], s[36:37] op_sel_hi:[1,1,0]
	v_pk_mul_f32 v[180:181], v[172:173], v[180:181]
	v_pk_mul_f32 v[182:183], v[174:175], v[182:183]
	v_pk_mul_f32 v[184:185], v[176:177], v[184:185]
	v_pk_mul_f32 v[186:187], v[178:179], v[186:187]
	v_pk_mul_f32 v[180:181], v[148:149], v[180:181]
	v_pk_mul_f32 v[182:183], v[150:151], v[182:183]
	v_pk_mul_f32 v[184:185], v[152:153], v[184:185]
	v_pk_mul_f32 v[186:187], v[154:155], v[186:187]
	v_max_f32_e32 v148, 0, v120
	v_max_f32_e32 v150, 0, v122
	v_max_f32_e32 v152, 0, v88
	v_max_f32_e32 v154, 0, v90
	v_max_f32_e32 v149, 0, v121
	v_max_f32_e32 v151, 0, v123
	v_max_f32_e32 v153, 0, v89
	v_max_f32_e32 v155, 0, v91
	v_fma_f32 v148, -|v120|, v180, v148
	v_fma_f32 v150, -|v122|, v182, v150
	v_fma_f32 v152, -|v88|, v184, v152
	v_fma_f32 v154, -|v90|, v186, v154
	v_fma_f32 v149, -|v121|, v181, v149
	v_fma_f32 v151, -|v123|, v183, v151
	v_fma_f32 v153, -|v89|, v185, v153
	v_fma_f32 v155, -|v91|, v187, v155
.LBB0_306:
	v_cvt_pk_bf16_f32 v148, v148, v149
	v_cvt_pk_bf16_f32 v149, v150, v151
	v_cvt_pk_bf16_f32 v150, v152, v153
	v_add_co_u32_e32 v152, vcc, 0x4000, v146
	v_cvt_pk_bf16_f32 v151, v154, v155
	s_mov_b64 s[80:81], -1
	s_nop 0
	v_addc_co_u32_e32 v153, vcc, 0, v147, vcc
	s_and_b64 vcc, exec, s[0:1]
	global_store_dwordx4 v[152:153], v[148:151], off
	s_cbranch_vccnz .LBB0_308
	v_mov_b32_e32 v188, 0xbfb8aa3b
	v_pk_mul_f32 v[148:149], v[56:57], v[188:189] op_sel_hi:[1,0]
	v_pk_mul_f32 v[150:151], v[58:59], v[188:189] op_sel_hi:[1,0]
	v_pk_mul_f32 v[152:153], v[24:25], v[188:189] op_sel_hi:[1,0]
	v_pk_mul_f32 v[154:155], v[26:27], v[188:189] op_sel_hi:[1,0]
	v_exp_f32_e32 v148, v148
	v_exp_f32_e32 v150, v150
	v_exp_f32_e32 v152, v152
	v_exp_f32_e32 v154, v154
	v_exp_f32_e32 v149, v149
	v_exp_f32_e32 v151, v151
	v_exp_f32_e32 v153, v153
	v_exp_f32_e32 v155, v155
	v_pk_add_f32 v[148:149], v[148:149], 1.0 op_sel_hi:[1,0]
	v_pk_add_f32 v[150:151], v[150:151], 1.0 op_sel_hi:[1,0]
	v_pk_add_f32 v[152:153], v[152:153], 1.0 op_sel_hi:[1,0]
	v_pk_add_f32 v[154:155], v[154:155], 1.0 op_sel_hi:[1,0]
	v_rcp_f32_e32 v148, v148
	v_rcp_f32_e32 v150, v150
	v_rcp_f32_e32 v152, v152
	v_rcp_f32_e32 v154, v154
	v_rcp_f32_e32 v149, v149
	v_rcp_f32_e32 v151, v151
	v_rcp_f32_e32 v153, v153
	v_rcp_f32_e32 v155, v155
	v_pk_mul_f32 v[148:149], v[56:57], v[148:149]
	v_pk_mul_f32 v[150:151], v[58:59], v[150:151]
	v_pk_mul_f32 v[152:153], v[24:25], v[152:153]
	v_pk_mul_f32 v[154:155], v[26:27], v[154:155]
	s_mov_b64 s[80:81], 0
.LBB0_308:
	s_andn2_b64 vcc, exec, s[80:81]
	s_cbranch_vccnz .LBB0_310
	v_mov_b32_e32 v188, s12
	v_fma_f32 v172, |v56|, s8, 1.0
	v_fma_f32 v174, |v58|, s8, 1.0
	v_fma_f32 v176, |v24|, s8, 1.0
	v_fma_f32 v178, |v26|, s8, 1.0
	v_fma_f32 v173, |v57|, s8, 1.0
	v_fma_f32 v175, |v59|, s8, 1.0
	v_fma_f32 v177, |v25|, s8, 1.0
	v_fma_f32 v179, |v27|, s8, 1.0
	v_pk_mul_f32 v[148:149], v[56:57], v[56:57]
	v_pk_mul_f32 v[150:151], v[58:59], v[58:59]
	v_pk_mul_f32 v[152:153], v[24:25], v[24:25]
	v_pk_mul_f32 v[154:155], v[26:27], v[26:27]
	v_rcp_f32_e32 v172, v172
	v_rcp_f32_e32 v174, v174
	v_rcp_f32_e32 v176, v176
	v_rcp_f32_e32 v178, v178
	v_rcp_f32_e32 v173, v173
	v_rcp_f32_e32 v175, v175
	v_rcp_f32_e32 v177, v177
	v_rcp_f32_e32 v179, v179
	v_pk_mul_f32 v[148:149], v[148:149], s[54:55] op_sel_hi:[1,0]
	v_pk_mul_f32 v[150:151], v[150:151], s[54:55] op_sel_hi:[1,0]
	v_pk_mul_f32 v[152:153], v[152:153], s[54:55] op_sel_hi:[1,0]
	v_pk_mul_f32 v[154:155], v[154:155], s[54:55] op_sel_hi:[1,0]
	v_pk_fma_f32 v[180:181], v[172:173], s[10:11], v[188:189] op_sel_hi:[1,0,0]
	v_pk_fma_f32 v[182:183], v[174:175], s[10:11], v[188:189] op_sel_hi:[1,0,0]
	v_pk_fma_f32 v[184:185], v[176:177], s[10:11], v[188:189] op_sel_hi:[1,0,0]
	v_pk_fma_f32 v[186:187], v[178:179], s[10:11], v[188:189] op_sel_hi:[1,0,0]
	v_exp_f32_e32 v148, v148
	v_exp_f32_e32 v150, v150
	v_exp_f32_e32 v152, v152
	v_exp_f32_e32 v154, v154
	v_exp_f32_e32 v149, v149
	v_exp_f32_e32 v151, v151
	v_exp_f32_e32 v153, v153
	v_exp_f32_e32 v155, v155
	v_pk_fma_f32 v[180:181], v[172:173], v[180:181], s[14:15] op_sel_hi:[1,1,0]
	v_pk_fma_f32 v[182:183], v[174:175], v[182:183], s[14:15] op_sel_hi:[1,1,0]
	v_pk_fma_f32 v[184:185], v[176:177], v[184:185], s[14:15] op_sel_hi:[1,1,0]
	v_pk_fma_f32 v[186:187], v[178:179], v[186:187], s[14:15] op_sel_hi:[1,1,0]
	v_pk_fma_f32 v[180:181], v[172:173], v[180:181], s[18:19] op_sel_hi:[1,1,0]
	v_pk_fma_f32 v[182:183], v[174:175], v[182:183], s[18:19] op_sel_hi:[1,1,0]
	v_pk_fma_f32 v[184:185], v[176:177], v[184:185], s[18:19] op_sel_hi:[1,1,0]
	v_pk_fma_f32 v[186:187], v[178:179], v[186:187], s[18:19] op_sel_hi:[1,1,0]
	v_pk_fma_f32 v[180:181], v[172:173], v[180:181], s[36:37] op_sel_hi:[1,1,0]
	v_pk_fma_f32 v[182:183], v[174:175], v[182:183], s[36:37] op_sel_hi:[1,1,0]
	v_pk_fma_f32 v[184:185], v[176:177], v[184:185], s[36:37] op_sel_hi:[1,1,0]
	v_pk_fma_f32 v[186:187], v[178:179], v[186:187], s[36:37] op_sel_hi:[1,1,0]
	v_pk_mul_f32 v[180:181], v[172:173], v[180:181]
	v_pk_mul_f32 v[182:183], v[174:175], v[182:183]
	v_pk_mul_f32 v[184:185], v[176:177], v[184:185]
	v_pk_mul_f32 v[186:187], v[178:179], v[186:187]
	v_pk_mul_f32 v[180:181], v[148:149], v[180:181]
	v_pk_mul_f32 v[182:183], v[150:151], v[182:183]
	v_pk_mul_f32 v[184:185], v[152:153], v[184:185]
	v_pk_mul_f32 v[186:187], v[154:155], v[186:187]
	v_max_f32_e32 v148, 0, v56
	v_max_f32_e32 v150, 0, v58
	v_max_f32_e32 v152, 0, v24
	v_max_f32_e32 v154, 0, v26
	v_max_f32_e32 v149, 0, v57
	v_max_f32_e32 v151, 0, v59
	v_max_f32_e32 v153, 0, v25
	v_max_f32_e32 v155, 0, v27
	v_fma_f32 v148, -|v56|, v180, v148
	v_fma_f32 v150, -|v58|, v182, v150
	v_fma_f32 v152, -|v24|, v184, v152
	v_fma_f32 v154, -|v26|, v186, v154
	v_fma_f32 v149, -|v57|, v181, v149
	v_fma_f32 v151, -|v59|, v183, v151
	v_fma_f32 v153, -|v25|, v185, v153
	v_fma_f32 v155, -|v27|, v187, v155
.LBB0_310:
	v_cvt_pk_bf16_f32 v148, v148, v149
	v_cvt_pk_bf16_f32 v149, v150, v151
	v_cvt_pk_bf16_f32 v150, v152, v153
	v_add_co_u32_e32 v152, vcc, 0x4000, v146
	v_cvt_pk_bf16_f32 v151, v154, v155
	s_mov_b64 s[80:81], -1
	s_nop 0
	v_addc_co_u32_e32 v153, vcc, 0, v147, vcc
	s_and_b64 vcc, exec, s[0:1]
	global_store_dwordx4 v[152:153], v[148:151], off offset:256
	s_cbranch_vccnz .LBB0_312
	v_mov_b32_e32 v188, 0xbfb8aa3b
	v_pk_mul_f32 v[148:149], v[116:117], v[188:189] op_sel_hi:[1,0]
	v_pk_mul_f32 v[150:151], v[118:119], v[188:189] op_sel_hi:[1,0]
	v_pk_mul_f32 v[152:153], v[84:85], v[188:189] op_sel_hi:[1,0]
	v_pk_mul_f32 v[154:155], v[86:87], v[188:189] op_sel_hi:[1,0]
	v_exp_f32_e32 v148, v148
	v_exp_f32_e32 v150, v150
	v_exp_f32_e32 v152, v152
	v_exp_f32_e32 v154, v154
	v_exp_f32_e32 v149, v149
	v_exp_f32_e32 v151, v151
	v_exp_f32_e32 v153, v153
	v_exp_f32_e32 v155, v155
	v_pk_add_f32 v[148:149], v[148:149], 1.0 op_sel_hi:[1,0]
	v_pk_add_f32 v[150:151], v[150:151], 1.0 op_sel_hi:[1,0]
	v_pk_add_f32 v[152:153], v[152:153], 1.0 op_sel_hi:[1,0]
	v_pk_add_f32 v[154:155], v[154:155], 1.0 op_sel_hi:[1,0]
	v_rcp_f32_e32 v148, v148
	v_rcp_f32_e32 v150, v150
	v_rcp_f32_e32 v152, v152
	v_rcp_f32_e32 v154, v154
	v_rcp_f32_e32 v149, v149
	v_rcp_f32_e32 v151, v151
	v_rcp_f32_e32 v153, v153
	v_rcp_f32_e32 v155, v155
	v_pk_mul_f32 v[148:149], v[116:117], v[148:149]
	v_pk_mul_f32 v[150:151], v[118:119], v[150:151]
	v_pk_mul_f32 v[152:153], v[84:85], v[152:153]
	v_pk_mul_f32 v[154:155], v[86:87], v[154:155]
	s_mov_b64 s[80:81], 0
.LBB0_312:
	s_andn2_b64 vcc, exec, s[80:81]
	s_cbranch_vccnz .LBB0_314
	v_mov_b32_e32 v188, s12
	v_fma_f32 v172, |v116|, s8, 1.0
	v_fma_f32 v174, |v118|, s8, 1.0
	v_fma_f32 v176, |v84|, s8, 1.0
	v_fma_f32 v178, |v86|, s8, 1.0
	v_fma_f32 v173, |v117|, s8, 1.0
	v_fma_f32 v175, |v119|, s8, 1.0
	v_fma_f32 v177, |v85|, s8, 1.0
	v_fma_f32 v179, |v87|, s8, 1.0
	v_pk_mul_f32 v[148:149], v[116:117], v[116:117]
	v_pk_mul_f32 v[150:151], v[118:119], v[118:119]
	v_pk_mul_f32 v[152:153], v[84:85], v[84:85]
	v_pk_mul_f32 v[154:155], v[86:87], v[86:87]
	v_rcp_f32_e32 v172, v172
	v_rcp_f32_e32 v174, v174
	v_rcp_f32_e32 v176, v176
	v_rcp_f32_e32 v178, v178
	v_rcp_f32_e32 v173, v173
	v_rcp_f32_e32 v175, v175
	v_rcp_f32_e32 v177, v177
	v_rcp_f32_e32 v179, v179
	v_pk_mul_f32 v[148:149], v[148:149], s[54:55] op_sel_hi:[1,0]
	v_pk_mul_f32 v[150:151], v[150:151], s[54:55] op_sel_hi:[1,0]
	v_pk_mul_f32 v[152:153], v[152:153], s[54:55] op_sel_hi:[1,0]
	v_pk_mul_f32 v[154:155], v[154:155], s[54:55] op_sel_hi:[1,0]
	v_pk_fma_f32 v[180:181], v[172:173], s[10:11], v[188:189] op_sel_hi:[1,0,0]
	v_pk_fma_f32 v[182:183], v[174:175], s[10:11], v[188:189] op_sel_hi:[1,0,0]
	v_pk_fma_f32 v[184:185], v[176:177], s[10:11], v[188:189] op_sel_hi:[1,0,0]
	v_pk_fma_f32 v[186:187], v[178:179], s[10:11], v[188:189] op_sel_hi:[1,0,0]
	v_exp_f32_e32 v148, v148
	v_exp_f32_e32 v150, v150
	v_exp_f32_e32 v152, v152
	v_exp_f32_e32 v154, v154
	v_exp_f32_e32 v149, v149
	v_exp_f32_e32 v151, v151
	v_exp_f32_e32 v153, v153
	v_exp_f32_e32 v155, v155
	v_pk_fma_f32 v[180:181], v[172:173], v[180:181], s[14:15] op_sel_hi:[1,1,0]
	v_pk_fma_f32 v[182:183], v[174:175], v[182:183], s[14:15] op_sel_hi:[1,1,0]
	v_pk_fma_f32 v[184:185], v[176:177], v[184:185], s[14:15] op_sel_hi:[1,1,0]
	v_pk_fma_f32 v[186:187], v[178:179], v[186:187], s[14:15] op_sel_hi:[1,1,0]
	v_pk_fma_f32 v[180:181], v[172:173], v[180:181], s[18:19] op_sel_hi:[1,1,0]
	v_pk_fma_f32 v[182:183], v[174:175], v[182:183], s[18:19] op_sel_hi:[1,1,0]
	v_pk_fma_f32 v[184:185], v[176:177], v[184:185], s[18:19] op_sel_hi:[1,1,0]
	v_pk_fma_f32 v[186:187], v[178:179], v[186:187], s[18:19] op_sel_hi:[1,1,0]
	v_pk_fma_f32 v[180:181], v[172:173], v[180:181], s[36:37] op_sel_hi:[1,1,0]
	v_pk_fma_f32 v[182:183], v[174:175], v[182:183], s[36:37] op_sel_hi:[1,1,0]
	v_pk_fma_f32 v[184:185], v[176:177], v[184:185], s[36:37] op_sel_hi:[1,1,0]
	v_pk_fma_f32 v[186:187], v[178:179], v[186:187], s[36:37] op_sel_hi:[1,1,0]
	v_pk_mul_f32 v[180:181], v[172:173], v[180:181]
	v_pk_mul_f32 v[182:183], v[174:175], v[182:183]
	v_pk_mul_f32 v[184:185], v[176:177], v[184:185]
	v_pk_mul_f32 v[186:187], v[178:179], v[186:187]
	v_pk_mul_f32 v[180:181], v[148:149], v[180:181]
	v_pk_mul_f32 v[182:183], v[150:151], v[182:183]
	v_pk_mul_f32 v[184:185], v[152:153], v[184:185]
	v_pk_mul_f32 v[186:187], v[154:155], v[186:187]
	v_max_f32_e32 v148, 0, v116
	v_max_f32_e32 v150, 0, v118
	v_max_f32_e32 v152, 0, v84
	v_max_f32_e32 v154, 0, v86
	v_max_f32_e32 v149, 0, v117
	v_max_f32_e32 v151, 0, v119
	v_max_f32_e32 v153, 0, v85
	v_max_f32_e32 v155, 0, v87
	v_fma_f32 v148, -|v116|, v180, v148
	v_fma_f32 v150, -|v118|, v182, v150
	v_fma_f32 v152, -|v84|, v184, v152
	v_fma_f32 v154, -|v86|, v186, v154
	v_fma_f32 v149, -|v117|, v181, v149
	v_fma_f32 v151, -|v119|, v183, v151
	v_fma_f32 v153, -|v85|, v185, v153
	v_fma_f32 v155, -|v87|, v187, v155
.LBB0_314:
	v_cvt_pk_bf16_f32 v148, v148, v149
	v_cvt_pk_bf16_f32 v149, v150, v151
	v_cvt_pk_bf16_f32 v150, v152, v153
	v_add_co_u32_e32 v152, vcc, 0x8000, v146
	v_cvt_pk_bf16_f32 v151, v154, v155
	s_mov_b64 s[80:81], -1
	s_nop 0
	v_addc_co_u32_e32 v153, vcc, 0, v147, vcc
	s_and_b64 vcc, exec, s[0:1]
	global_store_dwordx4 v[152:153], v[148:151], off
	s_cbranch_vccnz .LBB0_316
	v_mov_b32_e32 v188, 0xbfb8aa3b
	v_pk_mul_f32 v[148:149], v[52:53], v[188:189] op_sel_hi:[1,0]
	v_pk_mul_f32 v[150:151], v[54:55], v[188:189] op_sel_hi:[1,0]
	v_pk_mul_f32 v[152:153], v[20:21], v[188:189] op_sel_hi:[1,0]
	v_pk_mul_f32 v[154:155], v[22:23], v[188:189] op_sel_hi:[1,0]
	v_exp_f32_e32 v148, v148
	v_exp_f32_e32 v150, v150
	v_exp_f32_e32 v152, v152
	v_exp_f32_e32 v154, v154
	v_exp_f32_e32 v149, v149
	v_exp_f32_e32 v151, v151
	v_exp_f32_e32 v153, v153
	v_exp_f32_e32 v155, v155
	v_pk_add_f32 v[148:149], v[148:149], 1.0 op_sel_hi:[1,0]
	v_pk_add_f32 v[150:151], v[150:151], 1.0 op_sel_hi:[1,0]
	v_pk_add_f32 v[152:153], v[152:153], 1.0 op_sel_hi:[1,0]
	v_pk_add_f32 v[154:155], v[154:155], 1.0 op_sel_hi:[1,0]
	v_rcp_f32_e32 v148, v148
	v_rcp_f32_e32 v150, v150
	v_rcp_f32_e32 v152, v152
	v_rcp_f32_e32 v154, v154
	v_rcp_f32_e32 v149, v149
	v_rcp_f32_e32 v151, v151
	v_rcp_f32_e32 v153, v153
	v_rcp_f32_e32 v155, v155
	v_pk_mul_f32 v[148:149], v[52:53], v[148:149]
	v_pk_mul_f32 v[150:151], v[54:55], v[150:151]
	v_pk_mul_f32 v[152:153], v[20:21], v[152:153]
	v_pk_mul_f32 v[154:155], v[22:23], v[154:155]
	s_mov_b64 s[80:81], 0
.LBB0_316:
	s_andn2_b64 vcc, exec, s[80:81]
	s_cbranch_vccnz .LBB0_318
	v_mov_b32_e32 v188, s12
	v_fma_f32 v172, |v52|, s8, 1.0
	v_fma_f32 v174, |v54|, s8, 1.0
	v_fma_f32 v176, |v20|, s8, 1.0
	v_fma_f32 v178, |v22|, s8, 1.0
	v_fma_f32 v173, |v53|, s8, 1.0
	v_fma_f32 v175, |v55|, s8, 1.0
	v_fma_f32 v177, |v21|, s8, 1.0
	v_fma_f32 v179, |v23|, s8, 1.0
	v_pk_mul_f32 v[148:149], v[52:53], v[52:53]
	v_pk_mul_f32 v[150:151], v[54:55], v[54:55]
	v_pk_mul_f32 v[152:153], v[20:21], v[20:21]
	v_pk_mul_f32 v[154:155], v[22:23], v[22:23]
	v_rcp_f32_e32 v172, v172
	v_rcp_f32_e32 v174, v174
	v_rcp_f32_e32 v176, v176
	v_rcp_f32_e32 v178, v178
	v_rcp_f32_e32 v173, v173
	v_rcp_f32_e32 v175, v175
	v_rcp_f32_e32 v177, v177
	v_rcp_f32_e32 v179, v179
	v_pk_mul_f32 v[148:149], v[148:149], s[54:55] op_sel_hi:[1,0]
	v_pk_mul_f32 v[150:151], v[150:151], s[54:55] op_sel_hi:[1,0]
	v_pk_mul_f32 v[152:153], v[152:153], s[54:55] op_sel_hi:[1,0]
	v_pk_mul_f32 v[154:155], v[154:155], s[54:55] op_sel_hi:[1,0]
	v_pk_fma_f32 v[180:181], v[172:173], s[10:11], v[188:189] op_sel_hi:[1,0,0]
	v_pk_fma_f32 v[182:183], v[174:175], s[10:11], v[188:189] op_sel_hi:[1,0,0]
	v_pk_fma_f32 v[184:185], v[176:177], s[10:11], v[188:189] op_sel_hi:[1,0,0]
	v_pk_fma_f32 v[186:187], v[178:179], s[10:11], v[188:189] op_sel_hi:[1,0,0]
	v_exp_f32_e32 v148, v148
	v_exp_f32_e32 v150, v150
	v_exp_f32_e32 v152, v152
	v_exp_f32_e32 v154, v154
	v_exp_f32_e32 v149, v149
	v_exp_f32_e32 v151, v151
	v_exp_f32_e32 v153, v153
	v_exp_f32_e32 v155, v155
	v_pk_fma_f32 v[180:181], v[172:173], v[180:181], s[14:15] op_sel_hi:[1,1,0]
	v_pk_fma_f32 v[182:183], v[174:175], v[182:183], s[14:15] op_sel_hi:[1,1,0]
	v_pk_fma_f32 v[184:185], v[176:177], v[184:185], s[14:15] op_sel_hi:[1,1,0]
	v_pk_fma_f32 v[186:187], v[178:179], v[186:187], s[14:15] op_sel_hi:[1,1,0]
	v_pk_fma_f32 v[180:181], v[172:173], v[180:181], s[18:19] op_sel_hi:[1,1,0]
	v_pk_fma_f32 v[182:183], v[174:175], v[182:183], s[18:19] op_sel_hi:[1,1,0]
	v_pk_fma_f32 v[184:185], v[176:177], v[184:185], s[18:19] op_sel_hi:[1,1,0]
	v_pk_fma_f32 v[186:187], v[178:179], v[186:187], s[18:19] op_sel_hi:[1,1,0]
	v_pk_fma_f32 v[180:181], v[172:173], v[180:181], s[36:37] op_sel_hi:[1,1,0]
	v_pk_fma_f32 v[182:183], v[174:175], v[182:183], s[36:37] op_sel_hi:[1,1,0]
	v_pk_fma_f32 v[184:185], v[176:177], v[184:185], s[36:37] op_sel_hi:[1,1,0]
	v_pk_fma_f32 v[186:187], v[178:179], v[186:187], s[36:37] op_sel_hi:[1,1,0]
	v_pk_mul_f32 v[180:181], v[172:173], v[180:181]
	v_pk_mul_f32 v[182:183], v[174:175], v[182:183]
	v_pk_mul_f32 v[184:185], v[176:177], v[184:185]
	v_pk_mul_f32 v[186:187], v[178:179], v[186:187]
	v_pk_mul_f32 v[180:181], v[148:149], v[180:181]
	v_pk_mul_f32 v[182:183], v[150:151], v[182:183]
	v_pk_mul_f32 v[184:185], v[152:153], v[184:185]
	v_pk_mul_f32 v[186:187], v[154:155], v[186:187]
	v_max_f32_e32 v148, 0, v52
	v_max_f32_e32 v150, 0, v54
	v_max_f32_e32 v152, 0, v20
	v_max_f32_e32 v154, 0, v22
	v_max_f32_e32 v149, 0, v53
	v_max_f32_e32 v151, 0, v55
	v_max_f32_e32 v153, 0, v21
	v_max_f32_e32 v155, 0, v23
	v_fma_f32 v148, -|v52|, v180, v148
	v_fma_f32 v150, -|v54|, v182, v150
	v_fma_f32 v152, -|v20|, v184, v152
	v_fma_f32 v154, -|v22|, v186, v154
	v_fma_f32 v149, -|v53|, v181, v149
	v_fma_f32 v151, -|v55|, v183, v151
	v_fma_f32 v153, -|v21|, v185, v153
	v_fma_f32 v155, -|v23|, v187, v155
.LBB0_318:
	v_cvt_pk_bf16_f32 v148, v148, v149
	v_cvt_pk_bf16_f32 v149, v150, v151
	v_cvt_pk_bf16_f32 v150, v152, v153
	v_add_co_u32_e32 v152, vcc, 0x8000, v146
	v_cvt_pk_bf16_f32 v151, v154, v155
	s_mov_b64 s[80:81], -1
	s_nop 0
	v_addc_co_u32_e32 v153, vcc, 0, v147, vcc
	s_and_b64 vcc, exec, s[0:1]
	global_store_dwordx4 v[152:153], v[148:151], off offset:256
	s_cbranch_vccnz .LBB0_320
	v_mov_b32_e32 v188, 0xbfb8aa3b
	v_pk_mul_f32 v[148:149], v[112:113], v[188:189] op_sel_hi:[1,0]
	v_pk_mul_f32 v[150:151], v[114:115], v[188:189] op_sel_hi:[1,0]
	v_pk_mul_f32 v[152:153], v[80:81], v[188:189] op_sel_hi:[1,0]
	v_pk_mul_f32 v[154:155], v[82:83], v[188:189] op_sel_hi:[1,0]
	v_exp_f32_e32 v148, v148
	v_exp_f32_e32 v150, v150
	v_exp_f32_e32 v152, v152
	v_exp_f32_e32 v154, v154
	v_exp_f32_e32 v149, v149
	v_exp_f32_e32 v151, v151
	v_exp_f32_e32 v153, v153
	v_exp_f32_e32 v155, v155
	v_pk_add_f32 v[148:149], v[148:149], 1.0 op_sel_hi:[1,0]
	v_pk_add_f32 v[150:151], v[150:151], 1.0 op_sel_hi:[1,0]
	v_pk_add_f32 v[152:153], v[152:153], 1.0 op_sel_hi:[1,0]
	v_pk_add_f32 v[154:155], v[154:155], 1.0 op_sel_hi:[1,0]
	v_rcp_f32_e32 v148, v148
	v_rcp_f32_e32 v150, v150
	v_rcp_f32_e32 v152, v152
	v_rcp_f32_e32 v154, v154
	v_rcp_f32_e32 v149, v149
	v_rcp_f32_e32 v151, v151
	v_rcp_f32_e32 v153, v153
	v_rcp_f32_e32 v155, v155
	v_pk_mul_f32 v[148:149], v[112:113], v[148:149]
	v_pk_mul_f32 v[150:151], v[114:115], v[150:151]
	v_pk_mul_f32 v[152:153], v[80:81], v[152:153]
	v_pk_mul_f32 v[154:155], v[82:83], v[154:155]
	s_mov_b64 s[80:81], 0
.LBB0_320:
	s_andn2_b64 vcc, exec, s[80:81]
	s_cbranch_vccnz .LBB0_322
	v_mov_b32_e32 v188, s12
	v_fma_f32 v172, |v112|, s8, 1.0
	v_fma_f32 v174, |v114|, s8, 1.0
	v_fma_f32 v176, |v80|, s8, 1.0
	v_fma_f32 v178, |v82|, s8, 1.0
	v_fma_f32 v173, |v113|, s8, 1.0
	v_fma_f32 v175, |v115|, s8, 1.0
	v_fma_f32 v177, |v81|, s8, 1.0
	v_fma_f32 v179, |v83|, s8, 1.0
	v_pk_mul_f32 v[148:149], v[112:113], v[112:113]
	v_pk_mul_f32 v[150:151], v[114:115], v[114:115]
	v_pk_mul_f32 v[152:153], v[80:81], v[80:81]
	v_pk_mul_f32 v[154:155], v[82:83], v[82:83]
	v_rcp_f32_e32 v172, v172
	v_rcp_f32_e32 v174, v174
	v_rcp_f32_e32 v176, v176
	v_rcp_f32_e32 v178, v178
	v_rcp_f32_e32 v173, v173
	v_rcp_f32_e32 v175, v175
	v_rcp_f32_e32 v177, v177
	v_rcp_f32_e32 v179, v179
	v_pk_mul_f32 v[148:149], v[148:149], s[54:55] op_sel_hi:[1,0]
	v_pk_mul_f32 v[150:151], v[150:151], s[54:55] op_sel_hi:[1,0]
	v_pk_mul_f32 v[152:153], v[152:153], s[54:55] op_sel_hi:[1,0]
	v_pk_mul_f32 v[154:155], v[154:155], s[54:55] op_sel_hi:[1,0]
	v_pk_fma_f32 v[180:181], v[172:173], s[10:11], v[188:189] op_sel_hi:[1,0,0]
	v_pk_fma_f32 v[182:183], v[174:175], s[10:11], v[188:189] op_sel_hi:[1,0,0]
	v_pk_fma_f32 v[184:185], v[176:177], s[10:11], v[188:189] op_sel_hi:[1,0,0]
	v_pk_fma_f32 v[186:187], v[178:179], s[10:11], v[188:189] op_sel_hi:[1,0,0]
	v_exp_f32_e32 v148, v148
	v_exp_f32_e32 v150, v150
	v_exp_f32_e32 v152, v152
	v_exp_f32_e32 v154, v154
	v_exp_f32_e32 v149, v149
	v_exp_f32_e32 v151, v151
	v_exp_f32_e32 v153, v153
	v_exp_f32_e32 v155, v155
	v_pk_fma_f32 v[180:181], v[172:173], v[180:181], s[14:15] op_sel_hi:[1,1,0]
	v_pk_fma_f32 v[182:183], v[174:175], v[182:183], s[14:15] op_sel_hi:[1,1,0]
	v_pk_fma_f32 v[184:185], v[176:177], v[184:185], s[14:15] op_sel_hi:[1,1,0]
	v_pk_fma_f32 v[186:187], v[178:179], v[186:187], s[14:15] op_sel_hi:[1,1,0]
	v_pk_fma_f32 v[180:181], v[172:173], v[180:181], s[18:19] op_sel_hi:[1,1,0]
	v_pk_fma_f32 v[182:183], v[174:175], v[182:183], s[18:19] op_sel_hi:[1,1,0]
	v_pk_fma_f32 v[184:185], v[176:177], v[184:185], s[18:19] op_sel_hi:[1,1,0]
	v_pk_fma_f32 v[186:187], v[178:179], v[186:187], s[18:19] op_sel_hi:[1,1,0]
	v_pk_fma_f32 v[180:181], v[172:173], v[180:181], s[36:37] op_sel_hi:[1,1,0]
	v_pk_fma_f32 v[182:183], v[174:175], v[182:183], s[36:37] op_sel_hi:[1,1,0]
	v_pk_fma_f32 v[184:185], v[176:177], v[184:185], s[36:37] op_sel_hi:[1,1,0]
	v_pk_fma_f32 v[186:187], v[178:179], v[186:187], s[36:37] op_sel_hi:[1,1,0]
	v_pk_mul_f32 v[180:181], v[172:173], v[180:181]
	v_pk_mul_f32 v[182:183], v[174:175], v[182:183]
	v_pk_mul_f32 v[184:185], v[176:177], v[184:185]
	v_pk_mul_f32 v[186:187], v[178:179], v[186:187]
	v_pk_mul_f32 v[180:181], v[148:149], v[180:181]
	v_pk_mul_f32 v[182:183], v[150:151], v[182:183]
	v_pk_mul_f32 v[184:185], v[152:153], v[184:185]
	v_pk_mul_f32 v[186:187], v[154:155], v[186:187]
	v_max_f32_e32 v148, 0, v112
	v_max_f32_e32 v150, 0, v114
	v_max_f32_e32 v152, 0, v80
	v_max_f32_e32 v154, 0, v82
	v_max_f32_e32 v149, 0, v113
	v_max_f32_e32 v151, 0, v115
	v_max_f32_e32 v153, 0, v81
	v_max_f32_e32 v155, 0, v83
	v_fma_f32 v148, -|v112|, v180, v148
	v_fma_f32 v150, -|v114|, v182, v150
	v_fma_f32 v152, -|v80|, v184, v152
	v_fma_f32 v154, -|v82|, v186, v154
	v_fma_f32 v149, -|v113|, v181, v149
	v_fma_f32 v151, -|v115|, v183, v151
	v_fma_f32 v153, -|v81|, v185, v153
	v_fma_f32 v155, -|v83|, v187, v155
.LBB0_322:
	v_cvt_pk_bf16_f32 v148, v148, v149
	v_cvt_pk_bf16_f32 v149, v150, v151
	v_cvt_pk_bf16_f32 v150, v152, v153
	v_add_co_u32_e32 v152, vcc, 0xc000, v146
	v_cvt_pk_bf16_f32 v151, v154, v155
	s_mov_b64 s[80:81], -1
	s_nop 0
	v_addc_co_u32_e32 v153, vcc, 0, v147, vcc
	s_and_b64 vcc, exec, s[0:1]
	global_store_dwordx4 v[152:153], v[148:151], off
	s_cbranch_vccnz .LBB0_324
	v_mov_b32_e32 v188, 0xbfb8aa3b
	v_pk_mul_f32 v[148:149], v[48:49], v[188:189] op_sel_hi:[1,0]
	v_pk_mul_f32 v[150:151], v[50:51], v[188:189] op_sel_hi:[1,0]
	v_pk_mul_f32 v[152:153], v[16:17], v[188:189] op_sel_hi:[1,0]
	v_pk_mul_f32 v[154:155], v[18:19], v[188:189] op_sel_hi:[1,0]
	v_exp_f32_e32 v148, v148
	v_exp_f32_e32 v150, v150
	v_exp_f32_e32 v152, v152
	v_exp_f32_e32 v154, v154
	v_exp_f32_e32 v149, v149
	v_exp_f32_e32 v151, v151
	v_exp_f32_e32 v153, v153
	v_exp_f32_e32 v155, v155
	v_pk_add_f32 v[148:149], v[148:149], 1.0 op_sel_hi:[1,0]
	v_pk_add_f32 v[150:151], v[150:151], 1.0 op_sel_hi:[1,0]
	v_pk_add_f32 v[152:153], v[152:153], 1.0 op_sel_hi:[1,0]
	v_pk_add_f32 v[154:155], v[154:155], 1.0 op_sel_hi:[1,0]
	v_rcp_f32_e32 v148, v148
	v_rcp_f32_e32 v150, v150
	v_rcp_f32_e32 v152, v152
	v_rcp_f32_e32 v154, v154
	v_rcp_f32_e32 v149, v149
	v_rcp_f32_e32 v151, v151
	v_rcp_f32_e32 v153, v153
	v_rcp_f32_e32 v155, v155
	v_pk_mul_f32 v[148:149], v[48:49], v[148:149]
	v_pk_mul_f32 v[150:151], v[50:51], v[150:151]
	v_pk_mul_f32 v[152:153], v[16:17], v[152:153]
	v_pk_mul_f32 v[154:155], v[18:19], v[154:155]
	s_mov_b64 s[80:81], 0
.LBB0_324:
	s_andn2_b64 vcc, exec, s[80:81]
	s_cbranch_vccnz .LBB0_326
	v_mov_b32_e32 v188, s12
	v_fma_f32 v172, |v48|, s8, 1.0
	v_fma_f32 v174, |v50|, s8, 1.0
	v_fma_f32 v176, |v16|, s8, 1.0
	v_fma_f32 v178, |v18|, s8, 1.0
	v_fma_f32 v173, |v49|, s8, 1.0
	v_fma_f32 v175, |v51|, s8, 1.0
	v_fma_f32 v177, |v17|, s8, 1.0
	v_fma_f32 v179, |v19|, s8, 1.0
	v_pk_mul_f32 v[148:149], v[48:49], v[48:49]
	v_pk_mul_f32 v[150:151], v[50:51], v[50:51]
	v_pk_mul_f32 v[152:153], v[16:17], v[16:17]
	v_pk_mul_f32 v[154:155], v[18:19], v[18:19]
	v_rcp_f32_e32 v172, v172
	v_rcp_f32_e32 v174, v174
	v_rcp_f32_e32 v176, v176
	v_rcp_f32_e32 v178, v178
	v_rcp_f32_e32 v173, v173
	v_rcp_f32_e32 v175, v175
	v_rcp_f32_e32 v177, v177
	v_rcp_f32_e32 v179, v179
	v_pk_mul_f32 v[148:149], v[148:149], s[54:55] op_sel_hi:[1,0]
	v_pk_mul_f32 v[150:151], v[150:151], s[54:55] op_sel_hi:[1,0]
	v_pk_mul_f32 v[152:153], v[152:153], s[54:55] op_sel_hi:[1,0]
	v_pk_mul_f32 v[154:155], v[154:155], s[54:55] op_sel_hi:[1,0]
	v_pk_fma_f32 v[180:181], v[172:173], s[10:11], v[188:189] op_sel_hi:[1,0,0]
	v_pk_fma_f32 v[182:183], v[174:175], s[10:11], v[188:189] op_sel_hi:[1,0,0]
	v_pk_fma_f32 v[184:185], v[176:177], s[10:11], v[188:189] op_sel_hi:[1,0,0]
	v_pk_fma_f32 v[186:187], v[178:179], s[10:11], v[188:189] op_sel_hi:[1,0,0]
	v_exp_f32_e32 v148, v148
	v_exp_f32_e32 v150, v150
	v_exp_f32_e32 v152, v152
	v_exp_f32_e32 v154, v154
	v_exp_f32_e32 v149, v149
	v_exp_f32_e32 v151, v151
	v_exp_f32_e32 v153, v153
	v_exp_f32_e32 v155, v155
	v_pk_fma_f32 v[180:181], v[172:173], v[180:181], s[14:15] op_sel_hi:[1,1,0]
	v_pk_fma_f32 v[182:183], v[174:175], v[182:183], s[14:15] op_sel_hi:[1,1,0]
	v_pk_fma_f32 v[184:185], v[176:177], v[184:185], s[14:15] op_sel_hi:[1,1,0]
	v_pk_fma_f32 v[186:187], v[178:179], v[186:187], s[14:15] op_sel_hi:[1,1,0]
	v_pk_fma_f32 v[180:181], v[172:173], v[180:181], s[18:19] op_sel_hi:[1,1,0]
	v_pk_fma_f32 v[182:183], v[174:175], v[182:183], s[18:19] op_sel_hi:[1,1,0]
	v_pk_fma_f32 v[184:185], v[176:177], v[184:185], s[18:19] op_sel_hi:[1,1,0]
	v_pk_fma_f32 v[186:187], v[178:179], v[186:187], s[18:19] op_sel_hi:[1,1,0]
	v_pk_fma_f32 v[180:181], v[172:173], v[180:181], s[36:37] op_sel_hi:[1,1,0]
	v_pk_fma_f32 v[182:183], v[174:175], v[182:183], s[36:37] op_sel_hi:[1,1,0]
	v_pk_fma_f32 v[184:185], v[176:177], v[184:185], s[36:37] op_sel_hi:[1,1,0]
	v_pk_fma_f32 v[186:187], v[178:179], v[186:187], s[36:37] op_sel_hi:[1,1,0]
	v_pk_mul_f32 v[180:181], v[172:173], v[180:181]
	v_pk_mul_f32 v[182:183], v[174:175], v[182:183]
	v_pk_mul_f32 v[184:185], v[176:177], v[184:185]
	v_pk_mul_f32 v[186:187], v[178:179], v[186:187]
	v_pk_mul_f32 v[180:181], v[148:149], v[180:181]
	v_pk_mul_f32 v[182:183], v[150:151], v[182:183]
	v_pk_mul_f32 v[184:185], v[152:153], v[184:185]
	v_pk_mul_f32 v[186:187], v[154:155], v[186:187]
	v_max_f32_e32 v148, 0, v48
	v_max_f32_e32 v150, 0, v50
	v_max_f32_e32 v152, 0, v16
	v_max_f32_e32 v154, 0, v18
	v_max_f32_e32 v149, 0, v49
	v_max_f32_e32 v151, 0, v51
	v_max_f32_e32 v153, 0, v17
	v_max_f32_e32 v155, 0, v19
	v_fma_f32 v148, -|v48|, v180, v148
	v_fma_f32 v150, -|v50|, v182, v150
	v_fma_f32 v152, -|v16|, v184, v152
	v_fma_f32 v154, -|v18|, v186, v154
	v_fma_f32 v149, -|v49|, v181, v149
	v_fma_f32 v151, -|v51|, v183, v151
	v_fma_f32 v153, -|v17|, v185, v153
	v_fma_f32 v155, -|v19|, v187, v155
.LBB0_326:
	v_cvt_pk_bf16_f32 v148, v148, v149
	v_cvt_pk_bf16_f32 v149, v150, v151
	v_cvt_pk_bf16_f32 v150, v152, v153
	v_add_co_u32_e32 v152, vcc, 0xc000, v146
	v_cvt_pk_bf16_f32 v151, v154, v155
	s_mov_b64 s[80:81], -1
	s_nop 0
	v_addc_co_u32_e32 v153, vcc, 0, v147, vcc
	s_and_b64 vcc, exec, s[0:1]
	global_store_dwordx4 v[152:153], v[148:151], off offset:256
	s_cbranch_vccnz .LBB0_328
	v_mov_b32_e32 v188, 0xbfb8aa3b
	v_pk_mul_f32 v[148:149], v[108:109], v[188:189] op_sel_hi:[1,0]
	v_pk_mul_f32 v[150:151], v[110:111], v[188:189] op_sel_hi:[1,0]
	v_pk_mul_f32 v[152:153], v[76:77], v[188:189] op_sel_hi:[1,0]
	v_pk_mul_f32 v[154:155], v[78:79], v[188:189] op_sel_hi:[1,0]
	v_exp_f32_e32 v148, v148
	v_exp_f32_e32 v150, v150
	v_exp_f32_e32 v152, v152
	v_exp_f32_e32 v154, v154
	v_exp_f32_e32 v149, v149
	v_exp_f32_e32 v151, v151
	v_exp_f32_e32 v153, v153
	v_exp_f32_e32 v155, v155
	v_pk_add_f32 v[148:149], v[148:149], 1.0 op_sel_hi:[1,0]
	v_pk_add_f32 v[150:151], v[150:151], 1.0 op_sel_hi:[1,0]
	v_pk_add_f32 v[152:153], v[152:153], 1.0 op_sel_hi:[1,0]
	v_pk_add_f32 v[154:155], v[154:155], 1.0 op_sel_hi:[1,0]
	v_rcp_f32_e32 v148, v148
	v_rcp_f32_e32 v150, v150
	v_rcp_f32_e32 v152, v152
	v_rcp_f32_e32 v154, v154
	v_rcp_f32_e32 v149, v149
	v_rcp_f32_e32 v151, v151
	v_rcp_f32_e32 v153, v153
	v_rcp_f32_e32 v155, v155
	v_pk_mul_f32 v[148:149], v[108:109], v[148:149]
	v_pk_mul_f32 v[150:151], v[110:111], v[150:151]
	v_pk_mul_f32 v[152:153], v[76:77], v[152:153]
	v_pk_mul_f32 v[154:155], v[78:79], v[154:155]
	s_mov_b64 s[80:81], 0
.LBB0_328:
	s_andn2_b64 vcc, exec, s[80:81]
	s_cbranch_vccnz .LBB0_330
	v_mov_b32_e32 v188, s12
	v_fma_f32 v172, |v108|, s8, 1.0
	v_fma_f32 v174, |v110|, s8, 1.0
	v_fma_f32 v176, |v76|, s8, 1.0
	v_fma_f32 v178, |v78|, s8, 1.0
	v_fma_f32 v173, |v109|, s8, 1.0
	v_fma_f32 v175, |v111|, s8, 1.0
	v_fma_f32 v177, |v77|, s8, 1.0
	v_fma_f32 v179, |v79|, s8, 1.0
	v_pk_mul_f32 v[148:149], v[108:109], v[108:109]
	v_pk_mul_f32 v[150:151], v[110:111], v[110:111]
	v_pk_mul_f32 v[152:153], v[76:77], v[76:77]
	v_pk_mul_f32 v[154:155], v[78:79], v[78:79]
	v_rcp_f32_e32 v172, v172
	v_rcp_f32_e32 v174, v174
	v_rcp_f32_e32 v176, v176
	v_rcp_f32_e32 v178, v178
	v_rcp_f32_e32 v173, v173
	v_rcp_f32_e32 v175, v175
	v_rcp_f32_e32 v177, v177
	v_rcp_f32_e32 v179, v179
	v_pk_mul_f32 v[148:149], v[148:149], s[54:55] op_sel_hi:[1,0]
	v_pk_mul_f32 v[150:151], v[150:151], s[54:55] op_sel_hi:[1,0]
	v_pk_mul_f32 v[152:153], v[152:153], s[54:55] op_sel_hi:[1,0]
	v_pk_mul_f32 v[154:155], v[154:155], s[54:55] op_sel_hi:[1,0]
	v_pk_fma_f32 v[180:181], v[172:173], s[10:11], v[188:189] op_sel_hi:[1,0,0]
	v_pk_fma_f32 v[182:183], v[174:175], s[10:11], v[188:189] op_sel_hi:[1,0,0]
	v_pk_fma_f32 v[184:185], v[176:177], s[10:11], v[188:189] op_sel_hi:[1,0,0]
	v_pk_fma_f32 v[186:187], v[178:179], s[10:11], v[188:189] op_sel_hi:[1,0,0]
	v_exp_f32_e32 v148, v148
	v_exp_f32_e32 v150, v150
	v_exp_f32_e32 v152, v152
	v_exp_f32_e32 v154, v154
	v_exp_f32_e32 v149, v149
	v_exp_f32_e32 v151, v151
	v_exp_f32_e32 v153, v153
	v_exp_f32_e32 v155, v155
	v_pk_fma_f32 v[180:181], v[172:173], v[180:181], s[14:15] op_sel_hi:[1,1,0]
	v_pk_fma_f32 v[182:183], v[174:175], v[182:183], s[14:15] op_sel_hi:[1,1,0]
	v_pk_fma_f32 v[184:185], v[176:177], v[184:185], s[14:15] op_sel_hi:[1,1,0]
	v_pk_fma_f32 v[186:187], v[178:179], v[186:187], s[14:15] op_sel_hi:[1,1,0]
	v_pk_fma_f32 v[180:181], v[172:173], v[180:181], s[18:19] op_sel_hi:[1,1,0]
	v_pk_fma_f32 v[182:183], v[174:175], v[182:183], s[18:19] op_sel_hi:[1,1,0]
	v_pk_fma_f32 v[184:185], v[176:177], v[184:185], s[18:19] op_sel_hi:[1,1,0]
	v_pk_fma_f32 v[186:187], v[178:179], v[186:187], s[18:19] op_sel_hi:[1,1,0]
	v_pk_fma_f32 v[180:181], v[172:173], v[180:181], s[36:37] op_sel_hi:[1,1,0]
	v_pk_fma_f32 v[182:183], v[174:175], v[182:183], s[36:37] op_sel_hi:[1,1,0]
	v_pk_fma_f32 v[184:185], v[176:177], v[184:185], s[36:37] op_sel_hi:[1,1,0]
	v_pk_fma_f32 v[186:187], v[178:179], v[186:187], s[36:37] op_sel_hi:[1,1,0]
	v_pk_mul_f32 v[180:181], v[172:173], v[180:181]
	v_pk_mul_f32 v[182:183], v[174:175], v[182:183]
	v_pk_mul_f32 v[184:185], v[176:177], v[184:185]
	v_pk_mul_f32 v[186:187], v[178:179], v[186:187]
	v_pk_mul_f32 v[180:181], v[148:149], v[180:181]
	v_pk_mul_f32 v[182:183], v[150:151], v[182:183]
	v_pk_mul_f32 v[184:185], v[152:153], v[184:185]
	v_pk_mul_f32 v[186:187], v[154:155], v[186:187]
	v_max_f32_e32 v148, 0, v108
	v_max_f32_e32 v150, 0, v110
	v_max_f32_e32 v152, 0, v76
	v_max_f32_e32 v154, 0, v78
	v_max_f32_e32 v149, 0, v109
	v_max_f32_e32 v151, 0, v111
	v_max_f32_e32 v153, 0, v77
	v_max_f32_e32 v155, 0, v79
	v_fma_f32 v148, -|v108|, v180, v148
	v_fma_f32 v150, -|v110|, v182, v150
	v_fma_f32 v152, -|v76|, v184, v152
	v_fma_f32 v154, -|v78|, v186, v154
	v_fma_f32 v149, -|v109|, v181, v149
	v_fma_f32 v151, -|v111|, v183, v151
	v_fma_f32 v153, -|v77|, v185, v153
	v_fma_f32 v155, -|v79|, v187, v155
.LBB0_330:
	v_cvt_pk_bf16_f32 v148, v148, v149
	v_cvt_pk_bf16_f32 v149, v150, v151
	v_cvt_pk_bf16_f32 v150, v152, v153
	v_add_co_u32_e32 v152, vcc, 0x20000, v146
	v_cvt_pk_bf16_f32 v151, v154, v155
	s_mov_b64 s[80:81], -1
	s_nop 0
	v_addc_co_u32_e32 v153, vcc, 0, v147, vcc
	s_and_b64 vcc, exec, s[0:1]
	global_store_dwordx4 v[152:153], v[148:151], off
	s_cbranch_vccnz .LBB0_332
	v_mov_b32_e32 v188, 0xbfb8aa3b
	v_pk_mul_f32 v[148:149], v[44:45], v[188:189] op_sel_hi:[1,0]
	v_pk_mul_f32 v[150:151], v[46:47], v[188:189] op_sel_hi:[1,0]
	v_pk_mul_f32 v[152:153], v[12:13], v[188:189] op_sel_hi:[1,0]
	v_pk_mul_f32 v[154:155], v[14:15], v[188:189] op_sel_hi:[1,0]
	v_exp_f32_e32 v148, v148
	v_exp_f32_e32 v150, v150
	v_exp_f32_e32 v152, v152
	v_exp_f32_e32 v154, v154
	v_exp_f32_e32 v149, v149
	v_exp_f32_e32 v151, v151
	v_exp_f32_e32 v153, v153
	v_exp_f32_e32 v155, v155
	v_pk_add_f32 v[148:149], v[148:149], 1.0 op_sel_hi:[1,0]
	v_pk_add_f32 v[150:151], v[150:151], 1.0 op_sel_hi:[1,0]
	v_pk_add_f32 v[152:153], v[152:153], 1.0 op_sel_hi:[1,0]
	v_pk_add_f32 v[154:155], v[154:155], 1.0 op_sel_hi:[1,0]
	v_rcp_f32_e32 v148, v148
	v_rcp_f32_e32 v150, v150
	v_rcp_f32_e32 v152, v152
	v_rcp_f32_e32 v154, v154
	v_rcp_f32_e32 v149, v149
	v_rcp_f32_e32 v151, v151
	v_rcp_f32_e32 v153, v153
	v_rcp_f32_e32 v155, v155
	v_pk_mul_f32 v[148:149], v[44:45], v[148:149]
	v_pk_mul_f32 v[150:151], v[46:47], v[150:151]
	v_pk_mul_f32 v[152:153], v[12:13], v[152:153]
	v_pk_mul_f32 v[154:155], v[14:15], v[154:155]
	s_mov_b64 s[80:81], 0
.LBB0_332:
	s_andn2_b64 vcc, exec, s[80:81]
	s_cbranch_vccnz .LBB0_334
	v_mov_b32_e32 v188, s12
	v_fma_f32 v172, |v44|, s8, 1.0
	v_fma_f32 v174, |v46|, s8, 1.0
	v_fma_f32 v176, |v12|, s8, 1.0
	v_fma_f32 v178, |v14|, s8, 1.0
	v_fma_f32 v173, |v45|, s8, 1.0
	v_fma_f32 v175, |v47|, s8, 1.0
	v_fma_f32 v177, |v13|, s8, 1.0
	v_fma_f32 v179, |v15|, s8, 1.0
	v_pk_mul_f32 v[148:149], v[44:45], v[44:45]
	v_pk_mul_f32 v[150:151], v[46:47], v[46:47]
	v_pk_mul_f32 v[152:153], v[12:13], v[12:13]
	v_pk_mul_f32 v[154:155], v[14:15], v[14:15]
	v_rcp_f32_e32 v172, v172
	v_rcp_f32_e32 v174, v174
	v_rcp_f32_e32 v176, v176
	v_rcp_f32_e32 v178, v178
	v_rcp_f32_e32 v173, v173
	v_rcp_f32_e32 v175, v175
	v_rcp_f32_e32 v177, v177
	v_rcp_f32_e32 v179, v179
	v_pk_mul_f32 v[148:149], v[148:149], s[54:55] op_sel_hi:[1,0]
	v_pk_mul_f32 v[150:151], v[150:151], s[54:55] op_sel_hi:[1,0]
	v_pk_mul_f32 v[152:153], v[152:153], s[54:55] op_sel_hi:[1,0]
	v_pk_mul_f32 v[154:155], v[154:155], s[54:55] op_sel_hi:[1,0]
	v_pk_fma_f32 v[180:181], v[172:173], s[10:11], v[188:189] op_sel_hi:[1,0,0]
	v_pk_fma_f32 v[182:183], v[174:175], s[10:11], v[188:189] op_sel_hi:[1,0,0]
	v_pk_fma_f32 v[184:185], v[176:177], s[10:11], v[188:189] op_sel_hi:[1,0,0]
	v_pk_fma_f32 v[186:187], v[178:179], s[10:11], v[188:189] op_sel_hi:[1,0,0]
	v_exp_f32_e32 v148, v148
	v_exp_f32_e32 v150, v150
	v_exp_f32_e32 v152, v152
	v_exp_f32_e32 v154, v154
	v_exp_f32_e32 v149, v149
	v_exp_f32_e32 v151, v151
	v_exp_f32_e32 v153, v153
	v_exp_f32_e32 v155, v155
	v_pk_fma_f32 v[180:181], v[172:173], v[180:181], s[14:15] op_sel_hi:[1,1,0]
	v_pk_fma_f32 v[182:183], v[174:175], v[182:183], s[14:15] op_sel_hi:[1,1,0]
	v_pk_fma_f32 v[184:185], v[176:177], v[184:185], s[14:15] op_sel_hi:[1,1,0]
	v_pk_fma_f32 v[186:187], v[178:179], v[186:187], s[14:15] op_sel_hi:[1,1,0]
	v_pk_fma_f32 v[180:181], v[172:173], v[180:181], s[18:19] op_sel_hi:[1,1,0]
	v_pk_fma_f32 v[182:183], v[174:175], v[182:183], s[18:19] op_sel_hi:[1,1,0]
	v_pk_fma_f32 v[184:185], v[176:177], v[184:185], s[18:19] op_sel_hi:[1,1,0]
	v_pk_fma_f32 v[186:187], v[178:179], v[186:187], s[18:19] op_sel_hi:[1,1,0]
	v_pk_fma_f32 v[180:181], v[172:173], v[180:181], s[36:37] op_sel_hi:[1,1,0]
	v_pk_fma_f32 v[182:183], v[174:175], v[182:183], s[36:37] op_sel_hi:[1,1,0]
	v_pk_fma_f32 v[184:185], v[176:177], v[184:185], s[36:37] op_sel_hi:[1,1,0]
	v_pk_fma_f32 v[186:187], v[178:179], v[186:187], s[36:37] op_sel_hi:[1,1,0]
	v_pk_mul_f32 v[180:181], v[172:173], v[180:181]
	v_pk_mul_f32 v[182:183], v[174:175], v[182:183]
	v_pk_mul_f32 v[184:185], v[176:177], v[184:185]
	v_pk_mul_f32 v[186:187], v[178:179], v[186:187]
	v_pk_mul_f32 v[180:181], v[148:149], v[180:181]
	v_pk_mul_f32 v[182:183], v[150:151], v[182:183]
	v_pk_mul_f32 v[184:185], v[152:153], v[184:185]
	v_pk_mul_f32 v[186:187], v[154:155], v[186:187]
	v_max_f32_e32 v148, 0, v44
	v_max_f32_e32 v150, 0, v46
	v_max_f32_e32 v152, 0, v12
	v_max_f32_e32 v154, 0, v14
	v_max_f32_e32 v149, 0, v45
	v_max_f32_e32 v151, 0, v47
	v_max_f32_e32 v153, 0, v13
	v_max_f32_e32 v155, 0, v15
	v_fma_f32 v148, -|v44|, v180, v148
	v_fma_f32 v150, -|v46|, v182, v150
	v_fma_f32 v152, -|v12|, v184, v152
	v_fma_f32 v154, -|v14|, v186, v154
	v_fma_f32 v149, -|v45|, v181, v149
	v_fma_f32 v151, -|v47|, v183, v151
	v_fma_f32 v153, -|v13|, v185, v153
	v_fma_f32 v155, -|v15|, v187, v155
.LBB0_334:
	v_cvt_pk_bf16_f32 v148, v148, v149
	v_cvt_pk_bf16_f32 v149, v150, v151
	v_cvt_pk_bf16_f32 v150, v152, v153
	v_add_co_u32_e32 v152, vcc, 0x20000, v146
	v_cvt_pk_bf16_f32 v151, v154, v155
	s_mov_b64 s[80:81], -1
	s_nop 0
	v_addc_co_u32_e32 v153, vcc, 0, v147, vcc
	s_and_b64 vcc, exec, s[0:1]
	global_store_dwordx4 v[152:153], v[148:151], off offset:256
	s_cbranch_vccnz .LBB0_336
	v_mov_b32_e32 v188, 0xbfb8aa3b
	v_pk_mul_f32 v[148:149], v[104:105], v[188:189] op_sel_hi:[1,0]
	v_pk_mul_f32 v[150:151], v[106:107], v[188:189] op_sel_hi:[1,0]
	v_pk_mul_f32 v[152:153], v[72:73], v[188:189] op_sel_hi:[1,0]
	v_pk_mul_f32 v[154:155], v[74:75], v[188:189] op_sel_hi:[1,0]
	v_exp_f32_e32 v148, v148
	v_exp_f32_e32 v150, v150
	v_exp_f32_e32 v152, v152
	v_exp_f32_e32 v154, v154
	v_exp_f32_e32 v149, v149
	v_exp_f32_e32 v151, v151
	v_exp_f32_e32 v153, v153
	v_exp_f32_e32 v155, v155
	v_pk_add_f32 v[148:149], v[148:149], 1.0 op_sel_hi:[1,0]
	v_pk_add_f32 v[150:151], v[150:151], 1.0 op_sel_hi:[1,0]
	v_pk_add_f32 v[152:153], v[152:153], 1.0 op_sel_hi:[1,0]
	v_pk_add_f32 v[154:155], v[154:155], 1.0 op_sel_hi:[1,0]
	v_rcp_f32_e32 v148, v148
	v_rcp_f32_e32 v150, v150
	v_rcp_f32_e32 v152, v152
	v_rcp_f32_e32 v154, v154
	v_rcp_f32_e32 v149, v149
	v_rcp_f32_e32 v151, v151
	v_rcp_f32_e32 v153, v153
	v_rcp_f32_e32 v155, v155
	v_pk_mul_f32 v[148:149], v[104:105], v[148:149]
	v_pk_mul_f32 v[150:151], v[106:107], v[150:151]
	v_pk_mul_f32 v[152:153], v[72:73], v[152:153]
	v_pk_mul_f32 v[154:155], v[74:75], v[154:155]
	s_mov_b64 s[80:81], 0
.LBB0_336:
	s_andn2_b64 vcc, exec, s[80:81]
	s_cbranch_vccnz .LBB0_338
	v_mov_b32_e32 v188, s12
	v_fma_f32 v172, |v104|, s8, 1.0
	v_fma_f32 v174, |v106|, s8, 1.0
	v_fma_f32 v176, |v72|, s8, 1.0
	v_fma_f32 v178, |v74|, s8, 1.0
	v_fma_f32 v173, |v105|, s8, 1.0
	v_fma_f32 v175, |v107|, s8, 1.0
	v_fma_f32 v177, |v73|, s8, 1.0
	v_fma_f32 v179, |v75|, s8, 1.0
	v_pk_mul_f32 v[148:149], v[104:105], v[104:105]
	v_pk_mul_f32 v[150:151], v[106:107], v[106:107]
	v_pk_mul_f32 v[152:153], v[72:73], v[72:73]
	v_pk_mul_f32 v[154:155], v[74:75], v[74:75]
	v_rcp_f32_e32 v172, v172
	v_rcp_f32_e32 v174, v174
	v_rcp_f32_e32 v176, v176
	v_rcp_f32_e32 v178, v178
	v_rcp_f32_e32 v173, v173
	v_rcp_f32_e32 v175, v175
	v_rcp_f32_e32 v177, v177
	v_rcp_f32_e32 v179, v179
	v_pk_mul_f32 v[148:149], v[148:149], s[54:55] op_sel_hi:[1,0]
	v_pk_mul_f32 v[150:151], v[150:151], s[54:55] op_sel_hi:[1,0]
	v_pk_mul_f32 v[152:153], v[152:153], s[54:55] op_sel_hi:[1,0]
	v_pk_mul_f32 v[154:155], v[154:155], s[54:55] op_sel_hi:[1,0]
	v_pk_fma_f32 v[180:181], v[172:173], s[10:11], v[188:189] op_sel_hi:[1,0,0]
	v_pk_fma_f32 v[182:183], v[174:175], s[10:11], v[188:189] op_sel_hi:[1,0,0]
	v_pk_fma_f32 v[184:185], v[176:177], s[10:11], v[188:189] op_sel_hi:[1,0,0]
	v_pk_fma_f32 v[186:187], v[178:179], s[10:11], v[188:189] op_sel_hi:[1,0,0]
	v_exp_f32_e32 v148, v148
	v_exp_f32_e32 v150, v150
	v_exp_f32_e32 v152, v152
	v_exp_f32_e32 v154, v154
	v_exp_f32_e32 v149, v149
	v_exp_f32_e32 v151, v151
	v_exp_f32_e32 v153, v153
	v_exp_f32_e32 v155, v155
	v_pk_fma_f32 v[180:181], v[172:173], v[180:181], s[14:15] op_sel_hi:[1,1,0]
	v_pk_fma_f32 v[182:183], v[174:175], v[182:183], s[14:15] op_sel_hi:[1,1,0]
	v_pk_fma_f32 v[184:185], v[176:177], v[184:185], s[14:15] op_sel_hi:[1,1,0]
	v_pk_fma_f32 v[186:187], v[178:179], v[186:187], s[14:15] op_sel_hi:[1,1,0]
	v_pk_fma_f32 v[180:181], v[172:173], v[180:181], s[18:19] op_sel_hi:[1,1,0]
	v_pk_fma_f32 v[182:183], v[174:175], v[182:183], s[18:19] op_sel_hi:[1,1,0]
	v_pk_fma_f32 v[184:185], v[176:177], v[184:185], s[18:19] op_sel_hi:[1,1,0]
	v_pk_fma_f32 v[186:187], v[178:179], v[186:187], s[18:19] op_sel_hi:[1,1,0]
	v_pk_fma_f32 v[180:181], v[172:173], v[180:181], s[36:37] op_sel_hi:[1,1,0]
	v_pk_fma_f32 v[182:183], v[174:175], v[182:183], s[36:37] op_sel_hi:[1,1,0]
	v_pk_fma_f32 v[184:185], v[176:177], v[184:185], s[36:37] op_sel_hi:[1,1,0]
	v_pk_fma_f32 v[186:187], v[178:179], v[186:187], s[36:37] op_sel_hi:[1,1,0]
	v_pk_mul_f32 v[180:181], v[172:173], v[180:181]
	v_pk_mul_f32 v[182:183], v[174:175], v[182:183]
	v_pk_mul_f32 v[184:185], v[176:177], v[184:185]
	v_pk_mul_f32 v[186:187], v[178:179], v[186:187]
	v_pk_mul_f32 v[180:181], v[148:149], v[180:181]
	v_pk_mul_f32 v[182:183], v[150:151], v[182:183]
	v_pk_mul_f32 v[184:185], v[152:153], v[184:185]
	v_pk_mul_f32 v[186:187], v[154:155], v[186:187]
	v_max_f32_e32 v148, 0, v104
	v_max_f32_e32 v150, 0, v106
	v_max_f32_e32 v152, 0, v72
	v_max_f32_e32 v154, 0, v74
	v_max_f32_e32 v149, 0, v105
	v_max_f32_e32 v151, 0, v107
	v_max_f32_e32 v153, 0, v73
	v_max_f32_e32 v155, 0, v75
	v_fma_f32 v148, -|v104|, v180, v148
	v_fma_f32 v150, -|v106|, v182, v150
	v_fma_f32 v152, -|v72|, v184, v152
	v_fma_f32 v154, -|v74|, v186, v154
	v_fma_f32 v149, -|v105|, v181, v149
	v_fma_f32 v151, -|v107|, v183, v151
	v_fma_f32 v153, -|v73|, v185, v153
	v_fma_f32 v155, -|v75|, v187, v155
.LBB0_338:
	v_cvt_pk_bf16_f32 v148, v148, v149
	v_cvt_pk_bf16_f32 v149, v150, v151
	v_cvt_pk_bf16_f32 v150, v152, v153
	v_add_co_u32_e32 v152, vcc, 0x24000, v146
	v_cvt_pk_bf16_f32 v151, v154, v155
	s_mov_b64 s[80:81], -1
	s_nop 0
	v_addc_co_u32_e32 v153, vcc, 0, v147, vcc
	s_and_b64 vcc, exec, s[0:1]
	global_store_dwordx4 v[152:153], v[148:151], off
	s_cbranch_vccnz .LBB0_340
	v_mov_b32_e32 v188, 0xbfb8aa3b
	v_pk_mul_f32 v[148:149], v[40:41], v[188:189] op_sel_hi:[1,0]
	v_pk_mul_f32 v[150:151], v[42:43], v[188:189] op_sel_hi:[1,0]
	v_pk_mul_f32 v[152:153], v[8:9], v[188:189] op_sel_hi:[1,0]
	v_pk_mul_f32 v[154:155], v[10:11], v[188:189] op_sel_hi:[1,0]
	v_exp_f32_e32 v148, v148
	v_exp_f32_e32 v150, v150
	v_exp_f32_e32 v152, v152
	v_exp_f32_e32 v154, v154
	v_exp_f32_e32 v149, v149
	v_exp_f32_e32 v151, v151
	v_exp_f32_e32 v153, v153
	v_exp_f32_e32 v155, v155
	v_pk_add_f32 v[148:149], v[148:149], 1.0 op_sel_hi:[1,0]
	v_pk_add_f32 v[150:151], v[150:151], 1.0 op_sel_hi:[1,0]
	v_pk_add_f32 v[152:153], v[152:153], 1.0 op_sel_hi:[1,0]
	v_pk_add_f32 v[154:155], v[154:155], 1.0 op_sel_hi:[1,0]
	v_rcp_f32_e32 v148, v148
	v_rcp_f32_e32 v150, v150
	v_rcp_f32_e32 v152, v152
	v_rcp_f32_e32 v154, v154
	v_rcp_f32_e32 v149, v149
	v_rcp_f32_e32 v151, v151
	v_rcp_f32_e32 v153, v153
	v_rcp_f32_e32 v155, v155
	v_pk_mul_f32 v[148:149], v[40:41], v[148:149]
	v_pk_mul_f32 v[150:151], v[42:43], v[150:151]
	v_pk_mul_f32 v[152:153], v[8:9], v[152:153]
	v_pk_mul_f32 v[154:155], v[10:11], v[154:155]
	s_mov_b64 s[80:81], 0
.LBB0_340:
	s_andn2_b64 vcc, exec, s[80:81]
	s_cbranch_vccnz .LBB0_342
	v_mov_b32_e32 v188, s12
	v_fma_f32 v172, |v40|, s8, 1.0
	v_fma_f32 v174, |v42|, s8, 1.0
	v_fma_f32 v176, |v8|, s8, 1.0
	v_fma_f32 v178, |v10|, s8, 1.0
	v_fma_f32 v173, |v41|, s8, 1.0
	v_fma_f32 v175, |v43|, s8, 1.0
	v_fma_f32 v177, |v9|, s8, 1.0
	v_fma_f32 v179, |v11|, s8, 1.0
	v_pk_mul_f32 v[148:149], v[40:41], v[40:41]
	v_pk_mul_f32 v[150:151], v[42:43], v[42:43]
	v_pk_mul_f32 v[152:153], v[8:9], v[8:9]
	v_pk_mul_f32 v[154:155], v[10:11], v[10:11]
	v_rcp_f32_e32 v172, v172
	v_rcp_f32_e32 v174, v174
	v_rcp_f32_e32 v176, v176
	v_rcp_f32_e32 v178, v178
	v_rcp_f32_e32 v173, v173
	v_rcp_f32_e32 v175, v175
	v_rcp_f32_e32 v177, v177
	v_rcp_f32_e32 v179, v179
	v_pk_mul_f32 v[148:149], v[148:149], s[54:55] op_sel_hi:[1,0]
	v_pk_mul_f32 v[150:151], v[150:151], s[54:55] op_sel_hi:[1,0]
	v_pk_mul_f32 v[152:153], v[152:153], s[54:55] op_sel_hi:[1,0]
	v_pk_mul_f32 v[154:155], v[154:155], s[54:55] op_sel_hi:[1,0]
	v_pk_fma_f32 v[180:181], v[172:173], s[10:11], v[188:189] op_sel_hi:[1,0,0]
	v_pk_fma_f32 v[182:183], v[174:175], s[10:11], v[188:189] op_sel_hi:[1,0,0]
	v_pk_fma_f32 v[184:185], v[176:177], s[10:11], v[188:189] op_sel_hi:[1,0,0]
	v_pk_fma_f32 v[186:187], v[178:179], s[10:11], v[188:189] op_sel_hi:[1,0,0]
	v_exp_f32_e32 v148, v148
	v_exp_f32_e32 v150, v150
	v_exp_f32_e32 v152, v152
	v_exp_f32_e32 v154, v154
	v_exp_f32_e32 v149, v149
	v_exp_f32_e32 v151, v151
	v_exp_f32_e32 v153, v153
	v_exp_f32_e32 v155, v155
	v_pk_fma_f32 v[180:181], v[172:173], v[180:181], s[14:15] op_sel_hi:[1,1,0]
	v_pk_fma_f32 v[182:183], v[174:175], v[182:183], s[14:15] op_sel_hi:[1,1,0]
	v_pk_fma_f32 v[184:185], v[176:177], v[184:185], s[14:15] op_sel_hi:[1,1,0]
	v_pk_fma_f32 v[186:187], v[178:179], v[186:187], s[14:15] op_sel_hi:[1,1,0]
	v_pk_fma_f32 v[180:181], v[172:173], v[180:181], s[18:19] op_sel_hi:[1,1,0]
	v_pk_fma_f32 v[182:183], v[174:175], v[182:183], s[18:19] op_sel_hi:[1,1,0]
	v_pk_fma_f32 v[184:185], v[176:177], v[184:185], s[18:19] op_sel_hi:[1,1,0]
	v_pk_fma_f32 v[186:187], v[178:179], v[186:187], s[18:19] op_sel_hi:[1,1,0]
	v_pk_fma_f32 v[180:181], v[172:173], v[180:181], s[36:37] op_sel_hi:[1,1,0]
	v_pk_fma_f32 v[182:183], v[174:175], v[182:183], s[36:37] op_sel_hi:[1,1,0]
	v_pk_fma_f32 v[184:185], v[176:177], v[184:185], s[36:37] op_sel_hi:[1,1,0]
	v_pk_fma_f32 v[186:187], v[178:179], v[186:187], s[36:37] op_sel_hi:[1,1,0]
	v_pk_mul_f32 v[180:181], v[172:173], v[180:181]
	v_pk_mul_f32 v[182:183], v[174:175], v[182:183]
	v_pk_mul_f32 v[184:185], v[176:177], v[184:185]
	v_pk_mul_f32 v[186:187], v[178:179], v[186:187]
	v_pk_mul_f32 v[180:181], v[148:149], v[180:181]
	v_pk_mul_f32 v[182:183], v[150:151], v[182:183]
	v_pk_mul_f32 v[184:185], v[152:153], v[184:185]
	v_pk_mul_f32 v[186:187], v[154:155], v[186:187]
	v_max_f32_e32 v148, 0, v40
	v_max_f32_e32 v150, 0, v42
	v_max_f32_e32 v152, 0, v8
	v_max_f32_e32 v154, 0, v10
	v_max_f32_e32 v149, 0, v41
	v_max_f32_e32 v151, 0, v43
	v_max_f32_e32 v153, 0, v9
	v_max_f32_e32 v155, 0, v11
	v_fma_f32 v148, -|v40|, v180, v148
	v_fma_f32 v150, -|v42|, v182, v150
	v_fma_f32 v152, -|v8|, v184, v152
	v_fma_f32 v154, -|v10|, v186, v154
	v_fma_f32 v149, -|v41|, v181, v149
	v_fma_f32 v151, -|v43|, v183, v151
	v_fma_f32 v153, -|v9|, v185, v153
	v_fma_f32 v155, -|v11|, v187, v155
.LBB0_342:
	v_cvt_pk_bf16_f32 v148, v148, v149
	v_cvt_pk_bf16_f32 v149, v150, v151
	v_cvt_pk_bf16_f32 v150, v152, v153
	v_add_co_u32_e32 v152, vcc, 0x24000, v146
	v_cvt_pk_bf16_f32 v151, v154, v155
	s_mov_b64 s[80:81], -1
	s_nop 0
	v_addc_co_u32_e32 v153, vcc, 0, v147, vcc
	s_and_b64 vcc, exec, s[0:1]
	global_store_dwordx4 v[152:153], v[148:151], off offset:256
	s_cbranch_vccnz .LBB0_344
	v_mov_b32_e32 v188, 0xbfb8aa3b
	v_pk_mul_f32 v[148:149], v[100:101], v[188:189] op_sel_hi:[1,0]
	v_pk_mul_f32 v[150:151], v[102:103], v[188:189] op_sel_hi:[1,0]
	v_pk_mul_f32 v[152:153], v[68:69], v[188:189] op_sel_hi:[1,0]
	v_pk_mul_f32 v[154:155], v[70:71], v[188:189] op_sel_hi:[1,0]
	v_exp_f32_e32 v148, v148
	v_exp_f32_e32 v150, v150
	v_exp_f32_e32 v152, v152
	v_exp_f32_e32 v154, v154
	v_exp_f32_e32 v149, v149
	v_exp_f32_e32 v151, v151
	v_exp_f32_e32 v153, v153
	v_exp_f32_e32 v155, v155
	v_pk_add_f32 v[148:149], v[148:149], 1.0 op_sel_hi:[1,0]
	v_pk_add_f32 v[150:151], v[150:151], 1.0 op_sel_hi:[1,0]
	v_pk_add_f32 v[152:153], v[152:153], 1.0 op_sel_hi:[1,0]
	v_pk_add_f32 v[154:155], v[154:155], 1.0 op_sel_hi:[1,0]
	v_rcp_f32_e32 v148, v148
	v_rcp_f32_e32 v150, v150
	v_rcp_f32_e32 v152, v152
	v_rcp_f32_e32 v154, v154
	v_rcp_f32_e32 v149, v149
	v_rcp_f32_e32 v151, v151
	v_rcp_f32_e32 v153, v153
	v_rcp_f32_e32 v155, v155
	v_pk_mul_f32 v[148:149], v[100:101], v[148:149]
	v_pk_mul_f32 v[150:151], v[102:103], v[150:151]
	v_pk_mul_f32 v[152:153], v[68:69], v[152:153]
	v_pk_mul_f32 v[154:155], v[70:71], v[154:155]
	s_mov_b64 s[80:81], 0
.LBB0_344:
	s_andn2_b64 vcc, exec, s[80:81]
	s_cbranch_vccnz .LBB0_346
	v_mov_b32_e32 v188, s12
	v_fma_f32 v172, |v100|, s8, 1.0
	v_fma_f32 v174, |v102|, s8, 1.0
	v_fma_f32 v176, |v68|, s8, 1.0
	v_fma_f32 v178, |v70|, s8, 1.0
	v_fma_f32 v173, |v101|, s8, 1.0
	v_fma_f32 v175, |v103|, s8, 1.0
	v_fma_f32 v177, |v69|, s8, 1.0
	v_fma_f32 v179, |v71|, s8, 1.0
	v_pk_mul_f32 v[148:149], v[100:101], v[100:101]
	v_pk_mul_f32 v[150:151], v[102:103], v[102:103]
	v_pk_mul_f32 v[152:153], v[68:69], v[68:69]
	v_pk_mul_f32 v[154:155], v[70:71], v[70:71]
	v_rcp_f32_e32 v172, v172
	v_rcp_f32_e32 v174, v174
	v_rcp_f32_e32 v176, v176
	v_rcp_f32_e32 v178, v178
	v_rcp_f32_e32 v173, v173
	v_rcp_f32_e32 v175, v175
	v_rcp_f32_e32 v177, v177
	v_rcp_f32_e32 v179, v179
	v_pk_mul_f32 v[148:149], v[148:149], s[54:55] op_sel_hi:[1,0]
	v_pk_mul_f32 v[150:151], v[150:151], s[54:55] op_sel_hi:[1,0]
	v_pk_mul_f32 v[152:153], v[152:153], s[54:55] op_sel_hi:[1,0]
	v_pk_mul_f32 v[154:155], v[154:155], s[54:55] op_sel_hi:[1,0]
	v_pk_fma_f32 v[180:181], v[172:173], s[10:11], v[188:189] op_sel_hi:[1,0,0]
	v_pk_fma_f32 v[182:183], v[174:175], s[10:11], v[188:189] op_sel_hi:[1,0,0]
	v_pk_fma_f32 v[184:185], v[176:177], s[10:11], v[188:189] op_sel_hi:[1,0,0]
	v_pk_fma_f32 v[186:187], v[178:179], s[10:11], v[188:189] op_sel_hi:[1,0,0]
	v_exp_f32_e32 v148, v148
	v_exp_f32_e32 v150, v150
	v_exp_f32_e32 v152, v152
	v_exp_f32_e32 v154, v154
	v_exp_f32_e32 v149, v149
	v_exp_f32_e32 v151, v151
	v_exp_f32_e32 v153, v153
	v_exp_f32_e32 v155, v155
	v_pk_fma_f32 v[180:181], v[172:173], v[180:181], s[14:15] op_sel_hi:[1,1,0]
	v_pk_fma_f32 v[182:183], v[174:175], v[182:183], s[14:15] op_sel_hi:[1,1,0]
	v_pk_fma_f32 v[184:185], v[176:177], v[184:185], s[14:15] op_sel_hi:[1,1,0]
	v_pk_fma_f32 v[186:187], v[178:179], v[186:187], s[14:15] op_sel_hi:[1,1,0]
	v_pk_fma_f32 v[180:181], v[172:173], v[180:181], s[18:19] op_sel_hi:[1,1,0]
	v_pk_fma_f32 v[182:183], v[174:175], v[182:183], s[18:19] op_sel_hi:[1,1,0]
	v_pk_fma_f32 v[184:185], v[176:177], v[184:185], s[18:19] op_sel_hi:[1,1,0]
	v_pk_fma_f32 v[186:187], v[178:179], v[186:187], s[18:19] op_sel_hi:[1,1,0]
	v_pk_fma_f32 v[180:181], v[172:173], v[180:181], s[36:37] op_sel_hi:[1,1,0]
	v_pk_fma_f32 v[182:183], v[174:175], v[182:183], s[36:37] op_sel_hi:[1,1,0]
	v_pk_fma_f32 v[184:185], v[176:177], v[184:185], s[36:37] op_sel_hi:[1,1,0]
	v_pk_fma_f32 v[186:187], v[178:179], v[186:187], s[36:37] op_sel_hi:[1,1,0]
	v_pk_mul_f32 v[180:181], v[172:173], v[180:181]
	v_pk_mul_f32 v[182:183], v[174:175], v[182:183]
	v_pk_mul_f32 v[184:185], v[176:177], v[184:185]
	v_pk_mul_f32 v[186:187], v[178:179], v[186:187]
	v_pk_mul_f32 v[180:181], v[148:149], v[180:181]
	v_pk_mul_f32 v[182:183], v[150:151], v[182:183]
	v_pk_mul_f32 v[184:185], v[152:153], v[184:185]
	v_pk_mul_f32 v[186:187], v[154:155], v[186:187]
	v_max_f32_e32 v148, 0, v100
	v_max_f32_e32 v150, 0, v102
	v_max_f32_e32 v152, 0, v68
	v_max_f32_e32 v154, 0, v70
	v_max_f32_e32 v149, 0, v101
	v_max_f32_e32 v151, 0, v103
	v_max_f32_e32 v153, 0, v69
	v_max_f32_e32 v155, 0, v71
	v_fma_f32 v148, -|v100|, v180, v148
	v_fma_f32 v150, -|v102|, v182, v150
	v_fma_f32 v152, -|v68|, v184, v152
	v_fma_f32 v154, -|v70|, v186, v154
	v_fma_f32 v149, -|v101|, v181, v149
	v_fma_f32 v151, -|v103|, v183, v151
	v_fma_f32 v153, -|v69|, v185, v153
	v_fma_f32 v155, -|v71|, v187, v155
.LBB0_346:
	v_cvt_pk_bf16_f32 v148, v148, v149
	v_cvt_pk_bf16_f32 v149, v150, v151
	v_cvt_pk_bf16_f32 v150, v152, v153
	v_add_co_u32_e32 v152, vcc, 0x28000, v146
	v_cvt_pk_bf16_f32 v151, v154, v155
	s_mov_b64 s[80:81], -1
	s_nop 0
	v_addc_co_u32_e32 v153, vcc, 0, v147, vcc
	s_and_b64 vcc, exec, s[0:1]
	global_store_dwordx4 v[152:153], v[148:151], off
	s_cbranch_vccnz .LBB0_348
	v_mov_b32_e32 v188, 0xbfb8aa3b
	v_pk_mul_f32 v[148:149], v[36:37], v[188:189] op_sel_hi:[1,0]
	v_pk_mul_f32 v[150:151], v[38:39], v[188:189] op_sel_hi:[1,0]
	v_pk_mul_f32 v[152:153], v[4:5], v[188:189] op_sel_hi:[1,0]
	v_pk_mul_f32 v[154:155], v[6:7], v[188:189] op_sel_hi:[1,0]
	v_exp_f32_e32 v148, v148
	v_exp_f32_e32 v150, v150
	v_exp_f32_e32 v152, v152
	v_exp_f32_e32 v154, v154
	v_exp_f32_e32 v149, v149
	v_exp_f32_e32 v151, v151
	v_exp_f32_e32 v153, v153
	v_exp_f32_e32 v155, v155
	v_pk_add_f32 v[148:149], v[148:149], 1.0 op_sel_hi:[1,0]
	v_pk_add_f32 v[150:151], v[150:151], 1.0 op_sel_hi:[1,0]
	v_pk_add_f32 v[152:153], v[152:153], 1.0 op_sel_hi:[1,0]
	v_pk_add_f32 v[154:155], v[154:155], 1.0 op_sel_hi:[1,0]
	v_rcp_f32_e32 v148, v148
	v_rcp_f32_e32 v150, v150
	v_rcp_f32_e32 v152, v152
	v_rcp_f32_e32 v154, v154
	v_rcp_f32_e32 v149, v149
	v_rcp_f32_e32 v151, v151
	v_rcp_f32_e32 v153, v153
	v_rcp_f32_e32 v155, v155
	v_pk_mul_f32 v[148:149], v[36:37], v[148:149]
	v_pk_mul_f32 v[150:151], v[38:39], v[150:151]
	v_pk_mul_f32 v[152:153], v[4:5], v[152:153]
	v_pk_mul_f32 v[154:155], v[6:7], v[154:155]
	s_mov_b64 s[80:81], 0
.LBB0_348:
	s_andn2_b64 vcc, exec, s[80:81]
	s_cbranch_vccnz .LBB0_350
	v_mov_b32_e32 v188, s12
	v_fma_f32 v172, |v36|, s8, 1.0
	v_fma_f32 v174, |v38|, s8, 1.0
	v_fma_f32 v176, |v4|, s8, 1.0
	v_fma_f32 v178, |v6|, s8, 1.0
	v_fma_f32 v173, |v37|, s8, 1.0
	v_fma_f32 v175, |v39|, s8, 1.0
	v_fma_f32 v177, |v5|, s8, 1.0
	v_fma_f32 v179, |v7|, s8, 1.0
	v_pk_mul_f32 v[148:149], v[36:37], v[36:37]
	v_pk_mul_f32 v[150:151], v[38:39], v[38:39]
	v_pk_mul_f32 v[152:153], v[4:5], v[4:5]
	v_pk_mul_f32 v[154:155], v[6:7], v[6:7]
	v_rcp_f32_e32 v172, v172
	v_rcp_f32_e32 v174, v174
	v_rcp_f32_e32 v176, v176
	v_rcp_f32_e32 v178, v178
	v_rcp_f32_e32 v173, v173
	v_rcp_f32_e32 v175, v175
	v_rcp_f32_e32 v177, v177
	v_rcp_f32_e32 v179, v179
	v_pk_mul_f32 v[148:149], v[148:149], s[54:55] op_sel_hi:[1,0]
	v_pk_mul_f32 v[150:151], v[150:151], s[54:55] op_sel_hi:[1,0]
	v_pk_mul_f32 v[152:153], v[152:153], s[54:55] op_sel_hi:[1,0]
	v_pk_mul_f32 v[154:155], v[154:155], s[54:55] op_sel_hi:[1,0]
	v_pk_fma_f32 v[180:181], v[172:173], s[10:11], v[188:189] op_sel_hi:[1,0,0]
	v_pk_fma_f32 v[182:183], v[174:175], s[10:11], v[188:189] op_sel_hi:[1,0,0]
	v_pk_fma_f32 v[184:185], v[176:177], s[10:11], v[188:189] op_sel_hi:[1,0,0]
	v_pk_fma_f32 v[186:187], v[178:179], s[10:11], v[188:189] op_sel_hi:[1,0,0]
	v_exp_f32_e32 v148, v148
	v_exp_f32_e32 v150, v150
	v_exp_f32_e32 v152, v152
	v_exp_f32_e32 v154, v154
	v_exp_f32_e32 v149, v149
	v_exp_f32_e32 v151, v151
	v_exp_f32_e32 v153, v153
	v_exp_f32_e32 v155, v155
	v_pk_fma_f32 v[180:181], v[172:173], v[180:181], s[14:15] op_sel_hi:[1,1,0]
	v_pk_fma_f32 v[182:183], v[174:175], v[182:183], s[14:15] op_sel_hi:[1,1,0]
	v_pk_fma_f32 v[184:185], v[176:177], v[184:185], s[14:15] op_sel_hi:[1,1,0]
	v_pk_fma_f32 v[186:187], v[178:179], v[186:187], s[14:15] op_sel_hi:[1,1,0]
	v_pk_fma_f32 v[180:181], v[172:173], v[180:181], s[18:19] op_sel_hi:[1,1,0]
	v_pk_fma_f32 v[182:183], v[174:175], v[182:183], s[18:19] op_sel_hi:[1,1,0]
	v_pk_fma_f32 v[184:185], v[176:177], v[184:185], s[18:19] op_sel_hi:[1,1,0]
	v_pk_fma_f32 v[186:187], v[178:179], v[186:187], s[18:19] op_sel_hi:[1,1,0]
	v_pk_fma_f32 v[180:181], v[172:173], v[180:181], s[36:37] op_sel_hi:[1,1,0]
	v_pk_fma_f32 v[182:183], v[174:175], v[182:183], s[36:37] op_sel_hi:[1,1,0]
	v_pk_fma_f32 v[184:185], v[176:177], v[184:185], s[36:37] op_sel_hi:[1,1,0]
	v_pk_fma_f32 v[186:187], v[178:179], v[186:187], s[36:37] op_sel_hi:[1,1,0]
	v_pk_mul_f32 v[180:181], v[172:173], v[180:181]
	v_pk_mul_f32 v[182:183], v[174:175], v[182:183]
	v_pk_mul_f32 v[184:185], v[176:177], v[184:185]
	v_pk_mul_f32 v[186:187], v[178:179], v[186:187]
	v_pk_mul_f32 v[180:181], v[148:149], v[180:181]
	v_pk_mul_f32 v[182:183], v[150:151], v[182:183]
	v_pk_mul_f32 v[184:185], v[152:153], v[184:185]
	v_pk_mul_f32 v[186:187], v[154:155], v[186:187]
	v_max_f32_e32 v148, 0, v36
	v_max_f32_e32 v150, 0, v38
	v_max_f32_e32 v152, 0, v4
	v_max_f32_e32 v154, 0, v6
	v_max_f32_e32 v149, 0, v37
	v_max_f32_e32 v151, 0, v39
	v_max_f32_e32 v153, 0, v5
	v_max_f32_e32 v155, 0, v7
	v_fma_f32 v148, -|v36|, v180, v148
	v_fma_f32 v150, -|v38|, v182, v150
	v_fma_f32 v152, -|v4|, v184, v152
	v_fma_f32 v154, -|v6|, v186, v154
	v_fma_f32 v149, -|v37|, v181, v149
	v_fma_f32 v151, -|v39|, v183, v151
	v_fma_f32 v153, -|v5|, v185, v153
	v_fma_f32 v155, -|v7|, v187, v155
.LBB0_350:
	v_cvt_pk_bf16_f32 v148, v148, v149
	v_cvt_pk_bf16_f32 v149, v150, v151
	v_cvt_pk_bf16_f32 v150, v152, v153
	v_add_co_u32_e32 v152, vcc, 0x28000, v146
	v_cvt_pk_bf16_f32 v151, v154, v155
	s_mov_b64 s[80:81], -1
	s_nop 0
	v_addc_co_u32_e32 v153, vcc, 0, v147, vcc
	s_and_b64 vcc, exec, s[0:1]
	global_store_dwordx4 v[152:153], v[148:151], off offset:256
	s_cbranch_vccnz .LBB0_352
	v_mov_b32_e32 v188, 0xbfb8aa3b
	v_pk_mul_f32 v[148:149], v[96:97], v[188:189] op_sel_hi:[1,0]
	v_pk_mul_f32 v[150:151], v[98:99], v[188:189] op_sel_hi:[1,0]
	v_pk_mul_f32 v[152:153], v[64:65], v[188:189] op_sel_hi:[1,0]
	v_pk_mul_f32 v[154:155], v[66:67], v[188:189] op_sel_hi:[1,0]
	v_exp_f32_e32 v148, v148
	v_exp_f32_e32 v150, v150
	v_exp_f32_e32 v152, v152
	v_exp_f32_e32 v154, v154
	v_exp_f32_e32 v149, v149
	v_exp_f32_e32 v151, v151
	v_exp_f32_e32 v153, v153
	v_exp_f32_e32 v155, v155
	v_pk_add_f32 v[148:149], v[148:149], 1.0 op_sel_hi:[1,0]
	v_pk_add_f32 v[150:151], v[150:151], 1.0 op_sel_hi:[1,0]
	v_pk_add_f32 v[152:153], v[152:153], 1.0 op_sel_hi:[1,0]
	v_pk_add_f32 v[154:155], v[154:155], 1.0 op_sel_hi:[1,0]
	v_rcp_f32_e32 v148, v148
	v_rcp_f32_e32 v150, v150
	v_rcp_f32_e32 v152, v152
	v_rcp_f32_e32 v154, v154
	v_rcp_f32_e32 v149, v149
	v_rcp_f32_e32 v151, v151
	v_rcp_f32_e32 v153, v153
	v_rcp_f32_e32 v155, v155
	v_pk_mul_f32 v[148:149], v[96:97], v[148:149]
	v_pk_mul_f32 v[150:151], v[98:99], v[150:151]
	v_pk_mul_f32 v[152:153], v[64:65], v[152:153]
	v_pk_mul_f32 v[154:155], v[66:67], v[154:155]
	s_mov_b64 s[80:81], 0
.LBB0_352:
	s_andn2_b64 vcc, exec, s[80:81]
	s_cbranch_vccnz .LBB0_354
	v_mov_b32_e32 v188, s12
	v_fma_f32 v172, |v96|, s8, 1.0
	v_fma_f32 v174, |v98|, s8, 1.0
	v_fma_f32 v176, |v64|, s8, 1.0
	v_fma_f32 v178, |v66|, s8, 1.0
	v_fma_f32 v173, |v97|, s8, 1.0
	v_fma_f32 v175, |v99|, s8, 1.0
	v_fma_f32 v177, |v65|, s8, 1.0
	v_fma_f32 v179, |v67|, s8, 1.0
	v_pk_mul_f32 v[148:149], v[96:97], v[96:97]
	v_pk_mul_f32 v[150:151], v[98:99], v[98:99]
	v_pk_mul_f32 v[152:153], v[64:65], v[64:65]
	v_pk_mul_f32 v[154:155], v[66:67], v[66:67]
	v_rcp_f32_e32 v172, v172
	v_rcp_f32_e32 v174, v174
	v_rcp_f32_e32 v176, v176
	v_rcp_f32_e32 v178, v178
	v_rcp_f32_e32 v173, v173
	v_rcp_f32_e32 v175, v175
	v_rcp_f32_e32 v177, v177
	v_rcp_f32_e32 v179, v179
	v_pk_mul_f32 v[148:149], v[148:149], s[54:55] op_sel_hi:[1,0]
	v_pk_mul_f32 v[150:151], v[150:151], s[54:55] op_sel_hi:[1,0]
	v_pk_mul_f32 v[152:153], v[152:153], s[54:55] op_sel_hi:[1,0]
	v_pk_mul_f32 v[154:155], v[154:155], s[54:55] op_sel_hi:[1,0]
	v_pk_fma_f32 v[180:181], v[172:173], s[10:11], v[188:189] op_sel_hi:[1,0,0]
	v_pk_fma_f32 v[182:183], v[174:175], s[10:11], v[188:189] op_sel_hi:[1,0,0]
	v_pk_fma_f32 v[184:185], v[176:177], s[10:11], v[188:189] op_sel_hi:[1,0,0]
	v_pk_fma_f32 v[186:187], v[178:179], s[10:11], v[188:189] op_sel_hi:[1,0,0]
	v_exp_f32_e32 v148, v148
	v_exp_f32_e32 v150, v150
	v_exp_f32_e32 v152, v152
	v_exp_f32_e32 v154, v154
	v_exp_f32_e32 v149, v149
	v_exp_f32_e32 v151, v151
	v_exp_f32_e32 v153, v153
	v_exp_f32_e32 v155, v155
	v_pk_fma_f32 v[180:181], v[172:173], v[180:181], s[14:15] op_sel_hi:[1,1,0]
	v_pk_fma_f32 v[182:183], v[174:175], v[182:183], s[14:15] op_sel_hi:[1,1,0]
	v_pk_fma_f32 v[184:185], v[176:177], v[184:185], s[14:15] op_sel_hi:[1,1,0]
	v_pk_fma_f32 v[186:187], v[178:179], v[186:187], s[14:15] op_sel_hi:[1,1,0]
	v_pk_fma_f32 v[180:181], v[172:173], v[180:181], s[18:19] op_sel_hi:[1,1,0]
	v_pk_fma_f32 v[182:183], v[174:175], v[182:183], s[18:19] op_sel_hi:[1,1,0]
	v_pk_fma_f32 v[184:185], v[176:177], v[184:185], s[18:19] op_sel_hi:[1,1,0]
	v_pk_fma_f32 v[186:187], v[178:179], v[186:187], s[18:19] op_sel_hi:[1,1,0]
	v_pk_fma_f32 v[180:181], v[172:173], v[180:181], s[36:37] op_sel_hi:[1,1,0]
	v_pk_fma_f32 v[182:183], v[174:175], v[182:183], s[36:37] op_sel_hi:[1,1,0]
	v_pk_fma_f32 v[184:185], v[176:177], v[184:185], s[36:37] op_sel_hi:[1,1,0]
	v_pk_fma_f32 v[186:187], v[178:179], v[186:187], s[36:37] op_sel_hi:[1,1,0]
	v_pk_mul_f32 v[180:181], v[172:173], v[180:181]
	v_pk_mul_f32 v[182:183], v[174:175], v[182:183]
	v_pk_mul_f32 v[184:185], v[176:177], v[184:185]
	v_pk_mul_f32 v[186:187], v[178:179], v[186:187]
	v_pk_mul_f32 v[180:181], v[148:149], v[180:181]
	v_pk_mul_f32 v[182:183], v[150:151], v[182:183]
	v_pk_mul_f32 v[184:185], v[152:153], v[184:185]
	v_pk_mul_f32 v[186:187], v[154:155], v[186:187]
	v_max_f32_e32 v148, 0, v96
	v_max_f32_e32 v150, 0, v98
	v_max_f32_e32 v152, 0, v64
	v_max_f32_e32 v154, 0, v66
	v_max_f32_e32 v149, 0, v97
	v_max_f32_e32 v151, 0, v99
	v_max_f32_e32 v153, 0, v65
	v_max_f32_e32 v155, 0, v67
	v_fma_f32 v148, -|v96|, v180, v148
	v_fma_f32 v150, -|v98|, v182, v150
	v_fma_f32 v152, -|v64|, v184, v152
	v_fma_f32 v154, -|v66|, v186, v154
	v_fma_f32 v149, -|v97|, v181, v149
	v_fma_f32 v151, -|v99|, v183, v151
	v_fma_f32 v153, -|v65|, v185, v153
	v_fma_f32 v155, -|v67|, v187, v155
.LBB0_354:
	v_cvt_pk_bf16_f32 v148, v148, v149
	v_cvt_pk_bf16_f32 v149, v150, v151
	v_cvt_pk_bf16_f32 v150, v152, v153
	v_add_co_u32_e32 v152, vcc, 0x2c000, v146
	v_cvt_pk_bf16_f32 v151, v154, v155
	s_nop 1
	v_addc_co_u32_e32 v153, vcc, 0, v147, vcc
	s_and_b64 vcc, exec, s[0:1]
	s_mov_b64 s[0:1], -1
	global_store_dwordx4 v[152:153], v[148:151], off
	s_cbranch_vccnz .LBB0_356
	v_mov_b32_e32 v188, 0xbfb8aa3b
	v_pk_mul_f32 v[148:149], v[32:33], v[188:189] op_sel_hi:[1,0]
	v_pk_mul_f32 v[150:151], v[34:35], v[188:189] op_sel_hi:[1,0]
	v_pk_mul_f32 v[152:153], v[0:1], v[188:189] op_sel_hi:[1,0]
	v_pk_mul_f32 v[154:155], v[2:3], v[188:189] op_sel_hi:[1,0]
	v_exp_f32_e32 v148, v148
	v_exp_f32_e32 v150, v150
	v_exp_f32_e32 v152, v152
	v_exp_f32_e32 v154, v154
	v_exp_f32_e32 v149, v149
	v_exp_f32_e32 v151, v151
	v_exp_f32_e32 v153, v153
	v_exp_f32_e32 v155, v155
	v_pk_add_f32 v[148:149], v[148:149], 1.0 op_sel_hi:[1,0]
	v_pk_add_f32 v[150:151], v[150:151], 1.0 op_sel_hi:[1,0]
	v_pk_add_f32 v[152:153], v[152:153], 1.0 op_sel_hi:[1,0]
	v_pk_add_f32 v[154:155], v[154:155], 1.0 op_sel_hi:[1,0]
	v_rcp_f32_e32 v148, v148
	v_rcp_f32_e32 v150, v150
	v_rcp_f32_e32 v152, v152
	v_rcp_f32_e32 v154, v154
	v_rcp_f32_e32 v149, v149
	v_rcp_f32_e32 v151, v151
	v_rcp_f32_e32 v153, v153
	v_rcp_f32_e32 v155, v155
	v_pk_mul_f32 v[148:149], v[32:33], v[148:149]
	v_pk_mul_f32 v[150:151], v[34:35], v[150:151]
	v_pk_mul_f32 v[152:153], v[0:1], v[152:153]
	v_pk_mul_f32 v[154:155], v[2:3], v[154:155]
	s_mov_b64 s[0:1], 0
.LBB0_356:
	s_andn2_b64 vcc, exec, s[0:1]
	s_cbranch_vccnz .LBB0_358
	v_mov_b32_e32 v188, s12
	v_fma_f32 v172, |v32|, s8, 1.0
	v_fma_f32 v174, |v34|, s8, 1.0
	v_fma_f32 v176, |v0|, s8, 1.0
	v_fma_f32 v178, |v2|, s8, 1.0
	v_fma_f32 v173, |v33|, s8, 1.0
	v_fma_f32 v175, |v35|, s8, 1.0
	v_fma_f32 v177, |v1|, s8, 1.0
	v_fma_f32 v179, |v3|, s8, 1.0
	v_pk_mul_f32 v[148:149], v[32:33], v[32:33]
	v_pk_mul_f32 v[150:151], v[34:35], v[34:35]
	v_pk_mul_f32 v[152:153], v[0:1], v[0:1]
	v_pk_mul_f32 v[154:155], v[2:3], v[2:3]
	v_rcp_f32_e32 v172, v172
	v_rcp_f32_e32 v174, v174
	v_rcp_f32_e32 v176, v176
	v_rcp_f32_e32 v178, v178
	v_rcp_f32_e32 v173, v173
	v_rcp_f32_e32 v175, v175
	v_rcp_f32_e32 v177, v177
	v_rcp_f32_e32 v179, v179
	v_pk_mul_f32 v[148:149], v[148:149], s[54:55] op_sel_hi:[1,0]
	v_pk_mul_f32 v[150:151], v[150:151], s[54:55] op_sel_hi:[1,0]
	v_pk_mul_f32 v[152:153], v[152:153], s[54:55] op_sel_hi:[1,0]
	v_pk_mul_f32 v[154:155], v[154:155], s[54:55] op_sel_hi:[1,0]
	v_pk_fma_f32 v[180:181], v[172:173], s[10:11], v[188:189] op_sel_hi:[1,0,0]
	v_pk_fma_f32 v[182:183], v[174:175], s[10:11], v[188:189] op_sel_hi:[1,0,0]
	v_pk_fma_f32 v[184:185], v[176:177], s[10:11], v[188:189] op_sel_hi:[1,0,0]
	v_pk_fma_f32 v[186:187], v[178:179], s[10:11], v[188:189] op_sel_hi:[1,0,0]
	v_exp_f32_e32 v148, v148
	v_exp_f32_e32 v150, v150
	v_exp_f32_e32 v152, v152
	v_exp_f32_e32 v154, v154
	v_exp_f32_e32 v149, v149
	v_exp_f32_e32 v151, v151
	v_exp_f32_e32 v153, v153
	v_exp_f32_e32 v155, v155
	v_pk_fma_f32 v[180:181], v[172:173], v[180:181], s[14:15] op_sel_hi:[1,1,0]
	v_pk_fma_f32 v[182:183], v[174:175], v[182:183], s[14:15] op_sel_hi:[1,1,0]
	v_pk_fma_f32 v[184:185], v[176:177], v[184:185], s[14:15] op_sel_hi:[1,1,0]
	v_pk_fma_f32 v[186:187], v[178:179], v[186:187], s[14:15] op_sel_hi:[1,1,0]
	v_pk_fma_f32 v[180:181], v[172:173], v[180:181], s[18:19] op_sel_hi:[1,1,0]
	v_pk_fma_f32 v[182:183], v[174:175], v[182:183], s[18:19] op_sel_hi:[1,1,0]
	v_pk_fma_f32 v[184:185], v[176:177], v[184:185], s[18:19] op_sel_hi:[1,1,0]
	v_pk_fma_f32 v[186:187], v[178:179], v[186:187], s[18:19] op_sel_hi:[1,1,0]
	v_pk_fma_f32 v[180:181], v[172:173], v[180:181], s[36:37] op_sel_hi:[1,1,0]
	v_pk_fma_f32 v[182:183], v[174:175], v[182:183], s[36:37] op_sel_hi:[1,1,0]
	v_pk_fma_f32 v[184:185], v[176:177], v[184:185], s[36:37] op_sel_hi:[1,1,0]
	v_pk_fma_f32 v[186:187], v[178:179], v[186:187], s[36:37] op_sel_hi:[1,1,0]
	v_pk_mul_f32 v[180:181], v[172:173], v[180:181]
	v_pk_mul_f32 v[182:183], v[174:175], v[182:183]
	v_pk_mul_f32 v[184:185], v[176:177], v[184:185]
	v_pk_mul_f32 v[186:187], v[178:179], v[186:187]
	v_pk_mul_f32 v[180:181], v[148:149], v[180:181]
	v_pk_mul_f32 v[182:183], v[150:151], v[182:183]
	v_pk_mul_f32 v[184:185], v[152:153], v[184:185]
	v_pk_mul_f32 v[186:187], v[154:155], v[186:187]
	v_max_f32_e32 v148, 0, v32
	v_max_f32_e32 v150, 0, v34
	v_max_f32_e32 v152, 0, v0
	v_max_f32_e32 v154, 0, v2
	v_max_f32_e32 v149, 0, v33
	v_max_f32_e32 v151, 0, v35
	v_max_f32_e32 v153, 0, v1
	v_max_f32_e32 v155, 0, v3
	v_fma_f32 v148, -|v32|, v180, v148
	v_fma_f32 v150, -|v34|, v182, v150
	v_fma_f32 v152, -|v0|, v184, v152
	v_fma_f32 v154, -|v2|, v186, v154
	v_fma_f32 v149, -|v33|, v181, v149
	v_fma_f32 v151, -|v35|, v183, v151
	v_fma_f32 v153, -|v1|, v185, v153
	v_fma_f32 v155, -|v3|, v187, v155
